# GEMM K-loop: first LDS-DMA of the DMA-heavy load segments issued after 2 (not 8) ds_reads, remaining ds_reads interleaved between the DMAs
# baseline (speedup 1.0000x reference)
.LBB0_168:
	s_add_i32 s2, 0, 0x10000
	s_add_i32 s3, 0, 0x14000
	v_lshl_add_u64 v[168:169], v[152:153], 0, s[74:75]
	v_add_u32_e32 v180, s2, v162
	v_add_u32_e32 v196, s3, v162
	v_cndmask_b32_e32 v205, v169, v155, vcc
	v_cndmask_b32_e32 v204, v168, v0, vcc
	ds_read_b128 v[168:171], v180
	ds_read_b128 v[172:175], v180 offset:1024
	ds_read_b128 v[176:179], v180 offset:2048
	ds_read_b128 v[180:183], v180 offset:3072
	ds_read_b128 v[184:187], v196
	ds_read_b128 v[188:191], v196 offset:1024
	ds_read_b128 v[192:195], v196 offset:2048
	ds_read_b128 v[196:199], v196 offset:3072
	v_cndmask_b32_e32 v207, v151, v157, vcc
	v_cndmask_b32_e32 v206, v150, v154, vcc
	v_lshl_add_u64 v[238:239], v[152:153], 0, v[144:145]
	s_add_i32 m0, s13, 0xc000
	ds_read_b128 v[200:203], v166
	ds_read_b128 v[210:213], v166 offset:1024
	ds_read_b128 v[214:217], v166 offset:2048
	ds_read_b128 v[218:221], v166 offset:3072
	ds_read_b128 v[222:225], v166 offset:4096
	ds_read_b128 v[226:229], v166 offset:5120
	ds_read_b128 v[230:233], v166 offset:6144
	ds_read_b128 v[234:237], v166 offset:7168
	global_load_lds_dwordx4 v[238:239], off
	v_lshl_add_u64 v[238:239], v[238:239], 0, s[52:53]
	s_add_i32 m0, s13, 0xe000
	s_nop 0
	global_load_lds_dwordx4 v[238:239], off
	s_waitcnt vmcnt(8)
	s_waitcnt lgkmcnt(0)
	s_barrier
	s_setprio 1
	s_waitcnt lgkmcnt(0)
	v_mfma_f32_16x16x32_bf16 v[122:125], v[168:171], v[200:203], v[122:125]
	v_mfma_f32_16x16x32_bf16 v[126:129], v[176:179], v[200:203], v[126:129]
	v_mfma_f32_16x16x32_bf16 v[106:109], v[168:171], v[214:217], v[106:109]
	v_mfma_f32_16x16x32_bf16 v[110:113], v[176:179], v[214:217], v[110:113]
	v_mfma_f32_16x16x32_bf16 v[90:93], v[168:171], v[222:225], v[90:93]
	v_mfma_f32_16x16x32_bf16 v[94:97], v[176:179], v[222:225], v[94:97]
	v_mfma_f32_16x16x32_bf16 v[74:77], v[168:171], v[230:233], v[74:77]
	v_mfma_f32_16x16x32_bf16 v[78:81], v[176:179], v[230:233], v[78:81]
	v_mfma_f32_16x16x32_bf16 v[122:125], v[172:175], v[210:213], v[122:125]
	v_mfma_f32_16x16x32_bf16 v[126:129], v[180:183], v[210:213], v[126:129]
	v_mfma_f32_16x16x32_bf16 v[106:109], v[172:175], v[218:221], v[106:109]
	v_mfma_f32_16x16x32_bf16 v[110:113], v[180:183], v[218:221], v[110:113]
	v_mfma_f32_16x16x32_bf16 v[90:93], v[172:175], v[226:229], v[90:93]
	v_mfma_f32_16x16x32_bf16 v[94:97], v[180:183], v[226:229], v[94:97]
	v_mfma_f32_16x16x32_bf16 v[74:77], v[172:175], v[234:237], v[74:77]
	v_mfma_f32_16x16x32_bf16 v[78:81], v[180:183], v[234:237], v[78:81]
	s_setprio 0
	s_setprio 1
	v_mfma_f32_16x16x32_bf16 v[114:117], v[184:187], v[200:203], v[114:117]
	v_mfma_f32_16x16x32_bf16 v[118:121], v[192:195], v[200:203], v[118:121]
	v_mfma_f32_16x16x32_bf16 v[98:101], v[184:187], v[214:217], v[98:101]
	v_mfma_f32_16x16x32_bf16 v[102:105], v[192:195], v[214:217], v[102:105]
	v_mfma_f32_16x16x32_bf16 v[82:85], v[184:187], v[222:225], v[82:85]
	v_mfma_f32_16x16x32_bf16 v[86:89], v[192:195], v[222:225], v[86:89]
	v_mfma_f32_16x16x32_bf16 v[66:69], v[184:187], v[230:233], v[66:69]
	v_mfma_f32_16x16x32_bf16 v[70:73], v[192:195], v[230:233], v[70:73]
	v_mfma_f32_16x16x32_bf16 v[114:117], v[188:191], v[210:213], v[114:117]
	v_mfma_f32_16x16x32_bf16 v[118:121], v[196:199], v[210:213], v[118:121]
	v_mfma_f32_16x16x32_bf16 v[98:101], v[188:191], v[218:221], v[98:101]
	v_mfma_f32_16x16x32_bf16 v[102:105], v[196:199], v[218:221], v[102:105]
	v_mfma_f32_16x16x32_bf16 v[82:85], v[188:191], v[226:229], v[82:85]
	v_mfma_f32_16x16x32_bf16 v[86:89], v[196:199], v[226:229], v[86:89]
	v_mfma_f32_16x16x32_bf16 v[66:69], v[188:191], v[234:237], v[66:69]
	v_mfma_f32_16x16x32_bf16 v[70:73], v[196:199], v[234:237], v[70:73]
	s_setprio 0
	s_barrier
	s_add_i32 s2, s2, s22
	v_lshl_add_u64 v[206:207], v[206:207], 0, v[136:137]
	s_mov_b32 m0, s2
	ds_read_b128 v[200:203], v166 offset:16384
	ds_read_b128 v[210:213], v166 offset:17408
	global_load_lds_dwordx4 v[206:207], off
	v_lshl_add_u64 v[238:239], v[206:207], 0, s[52:53]
	s_add_i32 m0, s2, 0x2000
	s_add_i32 s2, s3, s22
	ds_read_b128 v[214:217], v166 offset:18432
	ds_read_b128 v[218:221], v166 offset:19456
	global_load_lds_dwordx4 v[238:239], off
	v_lshl_add_u64 v[238:239], v[206:207], 0, s[54:55]
	s_mov_b32 m0, s2
	v_lshl_add_u64 v[204:205], v[204:205], 0, v[134:135]
	ds_read_b128 v[222:225], v166 offset:20480
	ds_read_b128 v[226:229], v166 offset:21504
	global_load_lds_dwordx4 v[238:239], off
	v_lshl_add_u64 v[238:239], v[206:207], 0, s[56:57]
	s_add_i32 m0, s2, 0x2000
	s_nop 0
	ds_read_b128 v[230:233], v166 offset:22528
	ds_read_b128 v[234:237], v166 offset:23552
	global_load_lds_dwordx4 v[238:239], off
	s_mov_b32 m0, s13
	v_lshl_add_u64 v[238:239], v[204:205], 0, s[52:53]
	global_load_lds_dwordx4 v[204:205], off
	s_mov_b32 m0, s23
	s_nop 0
	global_load_lds_dwordx4 v[238:239], off
	s_waitcnt vmcnt(8)
	s_waitcnt lgkmcnt(0)
	s_barrier
	s_setprio 1
	s_waitcnt lgkmcnt(0)
	v_mfma_f32_16x16x32_bf16 v[58:61], v[168:171], v[200:203], v[58:61]
	v_mfma_f32_16x16x32_bf16 v[62:65], v[176:179], v[200:203], v[62:65]
	v_mfma_f32_16x16x32_bf16 v[42:45], v[168:171], v[214:217], v[42:45]
	v_mfma_f32_16x16x32_bf16 v[46:49], v[176:179], v[214:217], v[46:49]
	v_mfma_f32_16x16x32_bf16 v[26:29], v[168:171], v[222:225], v[26:29]
	v_mfma_f32_16x16x32_bf16 v[30:33], v[176:179], v[222:225], v[30:33]
	v_mfma_f32_16x16x32_bf16 v[10:13], v[168:171], v[230:233], v[10:13]
	v_mfma_f32_16x16x32_bf16 v[14:17], v[176:179], v[230:233], v[14:17]
	v_mfma_f32_16x16x32_bf16 v[58:61], v[172:175], v[210:213], v[58:61]
	v_mfma_f32_16x16x32_bf16 v[62:65], v[180:183], v[210:213], v[62:65]
	v_mfma_f32_16x16x32_bf16 v[42:45], v[172:175], v[218:221], v[42:45]
	v_mfma_f32_16x16x32_bf16 v[46:49], v[180:183], v[218:221], v[46:49]
	v_mfma_f32_16x16x32_bf16 v[26:29], v[172:175], v[226:229], v[26:29]
	v_mfma_f32_16x16x32_bf16 v[30:33], v[180:183], v[226:229], v[30:33]
	v_mfma_f32_16x16x32_bf16 v[10:13], v[172:175], v[234:237], v[10:13]
	v_mfma_f32_16x16x32_bf16 v[14:17], v[180:183], v[234:237], v[14:17]
	s_setprio 0
	s_setprio 1
	v_mfma_f32_16x16x32_bf16 v[50:53], v[184:187], v[200:203], v[50:53]
	v_mfma_f32_16x16x32_bf16 v[54:57], v[192:195], v[200:203], v[54:57]
	v_mfma_f32_16x16x32_bf16 v[34:37], v[184:187], v[214:217], v[34:37]
	v_mfma_f32_16x16x32_bf16 v[38:41], v[192:195], v[214:217], v[38:41]
	v_mfma_f32_16x16x32_bf16 v[18:21], v[184:187], v[222:225], v[18:21]
	v_mfma_f32_16x16x32_bf16 v[22:25], v[192:195], v[222:225], v[22:25]
	v_mfma_f32_16x16x32_bf16 v[2:5], v[184:187], v[230:233], v[2:5]
	v_mfma_f32_16x16x32_bf16 v[6:9], v[192:195], v[230:233], v[6:9]
	v_mfma_f32_16x16x32_bf16 v[50:53], v[188:191], v[210:213], v[50:53]
	v_mfma_f32_16x16x32_bf16 v[54:57], v[196:199], v[210:213], v[54:57]
	v_mfma_f32_16x16x32_bf16 v[34:37], v[188:191], v[218:221], v[34:37]
	v_mfma_f32_16x16x32_bf16 v[38:41], v[196:199], v[218:221], v[38:41]
	v_mfma_f32_16x16x32_bf16 v[18:21], v[188:191], v[226:229], v[18:21]
	v_mfma_f32_16x16x32_bf16 v[22:25], v[196:199], v[226:229], v[22:25]
	v_mfma_f32_16x16x32_bf16 v[2:5], v[188:191], v[234:237], v[2:5]
	v_mfma_f32_16x16x32_bf16 v[6:9], v[196:199], v[234:237], v[6:9]
	s_setprio 0
	s_barrier
	s_add_i32 s2, 0, 0x18000
	s_add_i32 s3, 0, 0x1c000
	v_add_u32_e32 v180, s2, v162
	v_add_u32_e32 v196, s3, v162
	ds_read_b128 v[168:171], v180
	ds_read_b128 v[172:175], v180 offset:1024
	ds_read_b128 v[176:179], v180 offset:2048
	ds_read_b128 v[180:183], v180 offset:3072
	ds_read_b128 v[184:187], v196
	ds_read_b128 v[188:191], v196 offset:1024
	ds_read_b128 v[192:195], v196 offset:2048
	ds_read_b128 v[196:199], v196 offset:3072
	s_mov_b32 m0, s24
	v_lshl_add_u64 v[238:239], v[204:205], 0, s[54:55]
	ds_read_b128 v[200:203], v166 offset:32768
	ds_read_b128 v[210:213], v166 offset:33792
	ds_read_b128 v[214:217], v166 offset:34816
	ds_read_b128 v[218:221], v166 offset:35840
	ds_read_b128 v[222:225], v166 offset:36864
	ds_read_b128 v[226:229], v166 offset:37888
	ds_read_b128 v[230:233], v166 offset:38912
	ds_read_b128 v[234:237], v166 offset:39936
	global_load_lds_dwordx4 v[238:239], off
	v_lshl_add_u64 v[238:239], v[204:205], 0, s[56:57]
	s_mov_b32 m0, s25
	s_nop 0
	global_load_lds_dwordx4 v[238:239], off
	s_waitcnt vmcnt(8)
	s_waitcnt lgkmcnt(0)
	s_barrier
	s_setprio 1
	s_waitcnt lgkmcnt(0)
	v_mfma_f32_16x16x32_bf16 v[122:125], v[168:171], v[200:203], v[122:125]
	v_mfma_f32_16x16x32_bf16 v[126:129], v[176:179], v[200:203], v[126:129]
	v_mfma_f32_16x16x32_bf16 v[106:109], v[168:171], v[214:217], v[106:109]
	v_mfma_f32_16x16x32_bf16 v[110:113], v[176:179], v[214:217], v[110:113]
	v_mfma_f32_16x16x32_bf16 v[90:93], v[168:171], v[222:225], v[90:93]
	v_mfma_f32_16x16x32_bf16 v[94:97], v[176:179], v[222:225], v[94:97]
	v_mfma_f32_16x16x32_bf16 v[74:77], v[168:171], v[230:233], v[74:77]
	v_mfma_f32_16x16x32_bf16 v[78:81], v[176:179], v[230:233], v[78:81]
	v_mfma_f32_16x16x32_bf16 v[122:125], v[172:175], v[210:213], v[122:125]
	v_mfma_f32_16x16x32_bf16 v[126:129], v[180:183], v[210:213], v[126:129]
	v_mfma_f32_16x16x32_bf16 v[106:109], v[172:175], v[218:221], v[106:109]
	v_mfma_f32_16x16x32_bf16 v[110:113], v[180:183], v[218:221], v[110:113]
	v_mfma_f32_16x16x32_bf16 v[90:93], v[172:175], v[226:229], v[90:93]
	v_mfma_f32_16x16x32_bf16 v[94:97], v[180:183], v[226:229], v[94:97]
	v_mfma_f32_16x16x32_bf16 v[74:77], v[172:175], v[234:237], v[74:77]
	v_mfma_f32_16x16x32_bf16 v[78:81], v[180:183], v[234:237], v[78:81]
	s_setprio 0
	s_setprio 1
	v_mfma_f32_16x16x32_bf16 v[114:117], v[184:187], v[200:203], v[114:117]
	v_mfma_f32_16x16x32_bf16 v[118:121], v[192:195], v[200:203], v[118:121]
	v_mfma_f32_16x16x32_bf16 v[98:101], v[184:187], v[214:217], v[98:101]
	v_mfma_f32_16x16x32_bf16 v[102:105], v[192:195], v[214:217], v[102:105]
	v_mfma_f32_16x16x32_bf16 v[82:85], v[184:187], v[222:225], v[82:85]
	v_mfma_f32_16x16x32_bf16 v[86:89], v[192:195], v[222:225], v[86:89]
	v_mfma_f32_16x16x32_bf16 v[66:69], v[184:187], v[230:233], v[66:69]
	v_mfma_f32_16x16x32_bf16 v[70:73], v[192:195], v[230:233], v[70:73]
	v_mfma_f32_16x16x32_bf16 v[114:117], v[188:191], v[210:213], v[114:117]
	v_mfma_f32_16x16x32_bf16 v[118:121], v[196:199], v[210:213], v[118:121]
	v_mfma_f32_16x16x32_bf16 v[98:101], v[188:191], v[218:221], v[98:101]
	v_mfma_f32_16x16x32_bf16 v[102:105], v[196:199], v[218:221], v[102:105]
	v_mfma_f32_16x16x32_bf16 v[82:85], v[188:191], v[226:229], v[82:85]
	v_mfma_f32_16x16x32_bf16 v[86:89], v[196:199], v[226:229], v[86:89]
	v_mfma_f32_16x16x32_bf16 v[66:69], v[188:191], v[234:237], v[66:69]
	v_mfma_f32_16x16x32_bf16 v[70:73], v[196:199], v[234:237], v[70:73]
	s_setprio 0
	s_barrier
	s_add_i32 s2, s2, s22
	v_lshl_add_u64 v[238:239], v[206:207], 0, s[62:63]
	s_mov_b32 m0, s2
	ds_read_b128 v[200:203], v166 offset:49152
	ds_read_b128 v[210:213], v166 offset:50176
	global_load_lds_dwordx4 v[238:239], off
	v_lshl_add_u64 v[238:239], v[206:207], 0, s[64:65]
	s_add_i32 m0, s2, 0x2000
	s_add_i32 s2, s3, s22
	ds_read_b128 v[214:217], v166 offset:51200
	ds_read_b128 v[218:221], v166 offset:52224
	global_load_lds_dwordx4 v[238:239], off
	v_lshl_add_u64 v[238:239], v[206:207], 0, s[66:67]
	s_mov_b32 m0, s2
	v_lshl_add_u64 v[206:207], v[206:207], 0, s[68:69]
	ds_read_b128 v[222:225], v166 offset:53248
	ds_read_b128 v[226:229], v166 offset:54272
	global_load_lds_dwordx4 v[238:239], off
	s_add_i32 m0, s2, 0x2000
	s_nop 0
	ds_read_b128 v[230:233], v166 offset:55296
	ds_read_b128 v[234:237], v166 offset:56320
	global_load_lds_dwordx4 v[206:207], off
	v_lshl_add_u64 v[206:207], v[204:205], 0, s[62:63]
	s_mov_b32 m0, s26
	v_lshl_add_u64 v[204:205], v[204:205], 0, s[64:65]
	global_load_lds_dwordx4 v[206:207], off
	s_mov_b32 m0, s27
	s_nop 0
	global_load_lds_dwordx4 v[204:205], off
	s_waitcnt vmcnt(8)
	s_waitcnt lgkmcnt(0)
	s_barrier
	s_setprio 1
	s_waitcnt lgkmcnt(0)
	v_mfma_f32_16x16x32_bf16 v[58:61], v[168:171], v[200:203], v[58:61]
	v_mfma_f32_16x16x32_bf16 v[62:65], v[176:179], v[200:203], v[62:65]
	v_mfma_f32_16x16x32_bf16 v[42:45], v[168:171], v[214:217], v[42:45]
	v_mfma_f32_16x16x32_bf16 v[46:49], v[176:179], v[214:217], v[46:49]
	v_mfma_f32_16x16x32_bf16 v[26:29], v[168:171], v[222:225], v[26:29]
	v_mfma_f32_16x16x32_bf16 v[30:33], v[176:179], v[222:225], v[30:33]
	v_mfma_f32_16x16x32_bf16 v[10:13], v[168:171], v[230:233], v[10:13]
	v_mfma_f32_16x16x32_bf16 v[14:17], v[176:179], v[230:233], v[14:17]
	v_mfma_f32_16x16x32_bf16 v[58:61], v[172:175], v[210:213], v[58:61]
	v_mfma_f32_16x16x32_bf16 v[62:65], v[180:183], v[210:213], v[62:65]
	v_mfma_f32_16x16x32_bf16 v[42:45], v[172:175], v[218:221], v[42:45]
	v_mfma_f32_16x16x32_bf16 v[46:49], v[180:183], v[218:221], v[46:49]
	v_mfma_f32_16x16x32_bf16 v[26:29], v[172:175], v[226:229], v[26:29]
	v_mfma_f32_16x16x32_bf16 v[30:33], v[180:183], v[226:229], v[30:33]
	v_mfma_f32_16x16x32_bf16 v[10:13], v[172:175], v[234:237], v[10:13]
	v_mfma_f32_16x16x32_bf16 v[14:17], v[180:183], v[234:237], v[14:17]
	s_setprio 0
	s_setprio 1
	v_mfma_f32_16x16x32_bf16 v[50:53], v[184:187], v[200:203], v[50:53]
	v_mfma_f32_16x16x32_bf16 v[54:57], v[192:195], v[200:203], v[54:57]
	v_mfma_f32_16x16x32_bf16 v[34:37], v[184:187], v[214:217], v[34:37]
	v_mfma_f32_16x16x32_bf16 v[38:41], v[192:195], v[214:217], v[38:41]
	v_mfma_f32_16x16x32_bf16 v[18:21], v[184:187], v[222:225], v[18:21]
	v_mfma_f32_16x16x32_bf16 v[22:25], v[192:195], v[222:225], v[22:25]
	v_mfma_f32_16x16x32_bf16 v[2:5], v[184:187], v[230:233], v[2:5]
	v_mfma_f32_16x16x32_bf16 v[6:9], v[192:195], v[230:233], v[6:9]
	v_mfma_f32_16x16x32_bf16 v[50:53], v[188:191], v[210:213], v[50:53]
	v_mfma_f32_16x16x32_bf16 v[54:57], v[196:199], v[210:213], v[54:57]
	v_mfma_f32_16x16x32_bf16 v[34:37], v[188:191], v[218:221], v[34:37]
	v_mfma_f32_16x16x32_bf16 v[38:41], v[196:199], v[218:221], v[38:41]
	v_mfma_f32_16x16x32_bf16 v[18:21], v[188:191], v[226:229], v[18:21]
	v_mfma_f32_16x16x32_bf16 v[22:25], v[196:199], v[226:229], v[22:25]
	v_mfma_f32_16x16x32_bf16 v[2:5], v[188:191], v[234:237], v[2:5]
	v_mfma_f32_16x16x32_bf16 v[6:9], v[196:199], v[234:237], v[6:9]
	s_setprio 0
	s_barrier
	s_add_i32 s1, s1, 2
	v_lshl_add_u64 v[152:153], v[152:153], 0, s[72:73]
	s_cmp_gt_u32 s1, 29
	v_lshl_add_u64 v[150:151], v[150:151], 0, s[72:73]
	s_cbranch_scc1 .LBB0_171

.LBB0_420:
	s_cmp_eq_u32 s11, 28
	s_cselect_b64 vcc, -1, 0
	s_add_i32 s13, 0, 0x10000
	v_add_u32_e32 v136, s13, v239
	s_add_i32 s15, 0, 0x14000
	ds_read_b128 v[138:141], v136
	ds_read_b128 v[142:145], v136 offset:1024
	ds_read_b128 v[146:149], v136 offset:2048
	ds_read_b128 v[150:153], v136 offset:3072
	v_add_u32_e32 v136, s15, v239
	ds_read_b128 v[154:157], v136
	ds_read_b128 v[158:161], v136 offset:1024
	ds_read_b128 v[162:165], v136 offset:2048
	ds_read_b128 v[166:169], v136 offset:3072
	s_mov_b32 s18, 0xfff00080
	s_mov_b32 s19, -1
	v_lshl_add_u64 v[170:171], v[134:135], 0, s[18:19]
	v_cndmask_b32_e32 v207, v171, v133, vcc
	v_cndmask_b32_e32 v206, v170, v0, vcc
	v_cndmask_b32_e32 v225, v131, v137, vcc
	v_cndmask_b32_e32 v224, v130, v132, vcc
	v_lshl_add_u64 v[226:227], v[134:135], 0, v[210:211]
	s_add_i32 m0, s23, 0xc000
	ds_read_b128 v[170:173], v251
	ds_read_b128 v[174:177], v251 offset:1024
	ds_read_b128 v[178:181], v251 offset:2048
	ds_read_b128 v[182:185], v251 offset:3072
	ds_read_b128 v[186:189], v251 offset:4096
	ds_read_b128 v[190:193], v251 offset:5120
	ds_read_b128 v[216:219], v251 offset:6144
	ds_read_b128 v[220:223], v251 offset:7168
	global_load_lds_dwordx4 v[226:227], off
	v_lshl_add_u64 v[226:227], v[226:227], 0, s[54:55]
	s_add_i32 m0, s23, 0xe000
	s_nop 0
	global_load_lds_dwordx4 v[226:227], off
	s_waitcnt vmcnt(8)
	s_waitcnt lgkmcnt(0)
	s_barrier
	s_setprio 1
	s_waitcnt lgkmcnt(0)
	v_mfma_f32_16x16x32_bf16 v[122:125], v[138:141], v[170:173], v[122:125]
	v_mfma_f32_16x16x32_bf16 v[126:129], v[146:149], v[170:173], v[126:129]
	v_mfma_f32_16x16x32_bf16 v[110:113], v[138:141], v[178:181], v[110:113]
	v_mfma_f32_16x16x32_bf16 v[106:109], v[146:149], v[178:181], v[106:109]
	v_mfma_f32_16x16x32_bf16 v[94:97], v[138:141], v[186:189], v[94:97]
	v_mfma_f32_16x16x32_bf16 v[90:93], v[146:149], v[186:189], v[90:93]
	v_mfma_f32_16x16x32_bf16 v[78:81], v[138:141], v[216:219], v[78:81]
	v_mfma_f32_16x16x32_bf16 v[74:77], v[146:149], v[216:219], v[74:77]
	v_mfma_f32_16x16x32_bf16 v[122:125], v[142:145], v[174:177], v[122:125]
	v_mfma_f32_16x16x32_bf16 v[126:129], v[150:153], v[174:177], v[126:129]
	v_mfma_f32_16x16x32_bf16 v[110:113], v[142:145], v[182:185], v[110:113]
	v_mfma_f32_16x16x32_bf16 v[106:109], v[150:153], v[182:185], v[106:109]
	v_mfma_f32_16x16x32_bf16 v[94:97], v[142:145], v[190:193], v[94:97]
	v_mfma_f32_16x16x32_bf16 v[90:93], v[150:153], v[190:193], v[90:93]
	v_mfma_f32_16x16x32_bf16 v[78:81], v[142:145], v[220:223], v[78:81]
	v_mfma_f32_16x16x32_bf16 v[74:77], v[150:153], v[220:223], v[74:77]
	s_setprio 0
	s_setprio 1
	v_mfma_f32_16x16x32_bf16 v[118:121], v[154:157], v[170:173], v[118:121]
	v_mfma_f32_16x16x32_bf16 v[114:117], v[162:165], v[170:173], v[114:117]
	v_mfma_f32_16x16x32_bf16 v[102:105], v[154:157], v[178:181], v[102:105]
	v_mfma_f32_16x16x32_bf16 v[98:101], v[162:165], v[178:181], v[98:101]
	v_mfma_f32_16x16x32_bf16 v[86:89], v[154:157], v[186:189], v[86:89]
	v_mfma_f32_16x16x32_bf16 v[82:85], v[162:165], v[186:189], v[82:85]
	v_mfma_f32_16x16x32_bf16 v[70:73], v[154:157], v[216:219], v[70:73]
	v_mfma_f32_16x16x32_bf16 v[66:69], v[162:165], v[216:219], v[66:69]
	v_mfma_f32_16x16x32_bf16 v[118:121], v[158:161], v[174:177], v[118:121]
	v_mfma_f32_16x16x32_bf16 v[114:117], v[166:169], v[174:177], v[114:117]
	v_mfma_f32_16x16x32_bf16 v[102:105], v[158:161], v[182:185], v[102:105]
	v_mfma_f32_16x16x32_bf16 v[98:101], v[166:169], v[182:185], v[98:101]
	v_mfma_f32_16x16x32_bf16 v[86:89], v[158:161], v[190:193], v[86:89]
	v_mfma_f32_16x16x32_bf16 v[82:85], v[166:169], v[190:193], v[82:85]
	v_mfma_f32_16x16x32_bf16 v[70:73], v[158:161], v[220:223], v[70:73]
	v_mfma_f32_16x16x32_bf16 v[66:69], v[166:169], v[220:223], v[66:69]
	s_setprio 0
	s_barrier
	s_add_i32 s13, s13, s22
	v_lshl_add_u64 v[224:225], v[224:225], 0, v[200:201]
	s_mov_b32 m0, s13
	ds_read_b128 v[170:173], v251 offset:16384
	ds_read_b128 v[174:177], v251 offset:17408
	global_load_lds_dwordx4 v[224:225], off
	v_lshl_add_u64 v[226:227], v[224:225], 0, s[52:53]
	s_add_i32 m0, s13, 0x2000
	s_add_i32 s13, s15, s22
	ds_read_b128 v[178:181], v251 offset:18432
	ds_read_b128 v[182:185], v251 offset:19456
	global_load_lds_dwordx4 v[226:227], off
	v_lshl_add_u64 v[226:227], v[224:225], 0, s[54:55]
	s_mov_b32 m0, s13
	v_lshl_add_u64 v[206:207], v[206:207], 0, v[198:199]
	ds_read_b128 v[186:189], v251 offset:20480
	ds_read_b128 v[190:193], v251 offset:21504
	global_load_lds_dwordx4 v[226:227], off
	v_lshl_add_u64 v[226:227], v[224:225], 0, s[56:57]
	s_add_i32 m0, s13, 0x2000
	s_nop 0
	ds_read_b128 v[216:219], v251 offset:22528
	ds_read_b128 v[220:223], v251 offset:23552
	global_load_lds_dwordx4 v[226:227], off
	s_mov_b32 m0, s23
	v_lshl_add_u64 v[226:227], v[206:207], 0, s[54:55]
	global_load_lds_dwordx4 v[206:207], off
	s_mov_b32 m0, s24
	s_nop 0
	global_load_lds_dwordx4 v[226:227], off
	s_waitcnt vmcnt(8)
	s_waitcnt lgkmcnt(0)
	s_barrier
	s_setprio 1
	s_waitcnt lgkmcnt(0)
	v_mfma_f32_16x16x32_bf16 v[62:65], v[138:141], v[170:173], v[62:65]
	v_mfma_f32_16x16x32_bf16 v[58:61], v[146:149], v[170:173], v[58:61]
	v_mfma_f32_16x16x32_bf16 v[46:49], v[138:141], v[178:181], v[46:49]
	v_mfma_f32_16x16x32_bf16 v[42:45], v[146:149], v[178:181], v[42:45]
	v_mfma_f32_16x16x32_bf16 v[30:33], v[138:141], v[186:189], v[30:33]
	v_mfma_f32_16x16x32_bf16 v[26:29], v[146:149], v[186:189], v[26:29]
	v_mfma_f32_16x16x32_bf16 v[14:17], v[138:141], v[216:219], v[14:17]
	v_mfma_f32_16x16x32_bf16 v[10:13], v[146:149], v[216:219], v[10:13]
	v_mfma_f32_16x16x32_bf16 v[62:65], v[142:145], v[174:177], v[62:65]
	v_mfma_f32_16x16x32_bf16 v[58:61], v[150:153], v[174:177], v[58:61]
	v_mfma_f32_16x16x32_bf16 v[46:49], v[142:145], v[182:185], v[46:49]
	v_mfma_f32_16x16x32_bf16 v[42:45], v[150:153], v[182:185], v[42:45]
	v_mfma_f32_16x16x32_bf16 v[30:33], v[142:145], v[190:193], v[30:33]
	v_mfma_f32_16x16x32_bf16 v[26:29], v[150:153], v[190:193], v[26:29]
	v_mfma_f32_16x16x32_bf16 v[14:17], v[142:145], v[220:223], v[14:17]
	v_mfma_f32_16x16x32_bf16 v[10:13], v[150:153], v[220:223], v[10:13]
	s_setprio 0
	s_setprio 1
	v_mfma_f32_16x16x32_bf16 v[54:57], v[154:157], v[170:173], v[54:57]
	v_mfma_f32_16x16x32_bf16 v[50:53], v[162:165], v[170:173], v[50:53]
	v_mfma_f32_16x16x32_bf16 v[38:41], v[154:157], v[178:181], v[38:41]
	v_mfma_f32_16x16x32_bf16 v[34:37], v[162:165], v[178:181], v[34:37]
	v_mfma_f32_16x16x32_bf16 v[22:25], v[154:157], v[186:189], v[22:25]
	v_mfma_f32_16x16x32_bf16 v[18:21], v[162:165], v[186:189], v[18:21]
	v_mfma_f32_16x16x32_bf16 v[6:9], v[154:157], v[216:219], v[6:9]
	v_mfma_f32_16x16x32_bf16 v[2:5], v[162:165], v[216:219], v[2:5]
	v_mfma_f32_16x16x32_bf16 v[54:57], v[158:161], v[174:177], v[54:57]
	v_mfma_f32_16x16x32_bf16 v[50:53], v[166:169], v[174:177], v[50:53]
	v_mfma_f32_16x16x32_bf16 v[38:41], v[158:161], v[182:185], v[38:41]
	v_mfma_f32_16x16x32_bf16 v[34:37], v[166:169], v[182:185], v[34:37]
	v_mfma_f32_16x16x32_bf16 v[22:25], v[158:161], v[190:193], v[22:25]
	v_mfma_f32_16x16x32_bf16 v[18:21], v[166:169], v[190:193], v[18:21]
	v_mfma_f32_16x16x32_bf16 v[6:9], v[158:161], v[220:223], v[6:9]
	v_mfma_f32_16x16x32_bf16 v[2:5], v[166:169], v[220:223], v[2:5]
	s_setprio 0
	s_barrier
	s_add_i32 s13, 0, 0x18000
	v_add_u32_e32 v136, s13, v239
	s_add_i32 s15, 0, 0x1c000
	ds_read_b128 v[138:141], v136
	ds_read_b128 v[142:145], v136 offset:1024
	ds_read_b128 v[146:149], v136 offset:2048
	ds_read_b128 v[150:153], v136 offset:3072
	v_add_u32_e32 v136, s15, v239
	ds_read_b128 v[154:157], v136
	ds_read_b128 v[158:161], v136 offset:1024
	ds_read_b128 v[162:165], v136 offset:2048
	ds_read_b128 v[166:169], v136 offset:3072
	s_mov_b32 m0, s25
	v_lshl_add_u64 v[226:227], v[206:207], 0, s[84:85]
	ds_read_b128 v[170:173], v251 offset:32768
	ds_read_b128 v[174:177], v251 offset:33792
	ds_read_b128 v[178:181], v251 offset:34816
	ds_read_b128 v[182:185], v251 offset:35840
	ds_read_b128 v[186:189], v251 offset:36864
	ds_read_b128 v[190:193], v251 offset:37888
	ds_read_b128 v[216:219], v251 offset:38912
	ds_read_b128 v[220:223], v251 offset:39936
	global_load_lds_dwordx4 v[226:227], off
	v_lshl_add_u64 v[226:227], v[206:207], 0, s[86:87]
	s_mov_b32 m0, s26
	s_nop 0
	global_load_lds_dwordx4 v[226:227], off
	s_waitcnt vmcnt(8)
	s_waitcnt lgkmcnt(0)
	s_barrier
	s_setprio 1
	s_waitcnt lgkmcnt(0)
	v_mfma_f32_16x16x32_bf16 v[122:125], v[138:141], v[170:173], v[122:125]
	v_mfma_f32_16x16x32_bf16 v[126:129], v[146:149], v[170:173], v[126:129]
	v_mfma_f32_16x16x32_bf16 v[110:113], v[138:141], v[178:181], v[110:113]
	v_mfma_f32_16x16x32_bf16 v[106:109], v[146:149], v[178:181], v[106:109]
	v_mfma_f32_16x16x32_bf16 v[94:97], v[138:141], v[186:189], v[94:97]
	v_mfma_f32_16x16x32_bf16 v[90:93], v[146:149], v[186:189], v[90:93]
	v_mfma_f32_16x16x32_bf16 v[78:81], v[138:141], v[216:219], v[78:81]
	v_mfma_f32_16x16x32_bf16 v[74:77], v[146:149], v[216:219], v[74:77]
	v_mfma_f32_16x16x32_bf16 v[122:125], v[142:145], v[174:177], v[122:125]
	v_mfma_f32_16x16x32_bf16 v[126:129], v[150:153], v[174:177], v[126:129]
	v_mfma_f32_16x16x32_bf16 v[110:113], v[142:145], v[182:185], v[110:113]
	v_mfma_f32_16x16x32_bf16 v[106:109], v[150:153], v[182:185], v[106:109]
	v_mfma_f32_16x16x32_bf16 v[94:97], v[142:145], v[190:193], v[94:97]
	v_mfma_f32_16x16x32_bf16 v[90:93], v[150:153], v[190:193], v[90:93]
	v_mfma_f32_16x16x32_bf16 v[78:81], v[142:145], v[220:223], v[78:81]
	v_mfma_f32_16x16x32_bf16 v[74:77], v[150:153], v[220:223], v[74:77]
	s_setprio 0
	s_setprio 1
	v_mfma_f32_16x16x32_bf16 v[118:121], v[154:157], v[170:173], v[118:121]
	v_mfma_f32_16x16x32_bf16 v[114:117], v[162:165], v[170:173], v[114:117]
	v_mfma_f32_16x16x32_bf16 v[102:105], v[154:157], v[178:181], v[102:105]
	v_mfma_f32_16x16x32_bf16 v[98:101], v[162:165], v[178:181], v[98:101]
	v_mfma_f32_16x16x32_bf16 v[86:89], v[154:157], v[186:189], v[86:89]
	v_mfma_f32_16x16x32_bf16 v[82:85], v[162:165], v[186:189], v[82:85]
	v_mfma_f32_16x16x32_bf16 v[70:73], v[154:157], v[216:219], v[70:73]
	v_mfma_f32_16x16x32_bf16 v[66:69], v[162:165], v[216:219], v[66:69]
	v_mfma_f32_16x16x32_bf16 v[118:121], v[158:161], v[174:177], v[118:121]
	v_mfma_f32_16x16x32_bf16 v[114:117], v[166:169], v[174:177], v[114:117]
	v_mfma_f32_16x16x32_bf16 v[102:105], v[158:161], v[182:185], v[102:105]
	v_mfma_f32_16x16x32_bf16 v[98:101], v[166:169], v[182:185], v[98:101]
	v_mfma_f32_16x16x32_bf16 v[86:89], v[158:161], v[190:193], v[86:89]
	v_mfma_f32_16x16x32_bf16 v[82:85], v[166:169], v[190:193], v[82:85]
	v_mfma_f32_16x16x32_bf16 v[70:73], v[158:161], v[220:223], v[70:73]
	v_mfma_f32_16x16x32_bf16 v[66:69], v[166:169], v[220:223], v[66:69]
	s_setprio 0
	s_barrier
	s_add_i32 s13, s13, s22
	v_lshl_add_u64 v[226:227], v[224:225], 0, s[62:63]
	s_mov_b32 m0, s13
	ds_read_b128 v[170:173], v251 offset:49152
	ds_read_b128 v[174:177], v251 offset:50176
	global_load_lds_dwordx4 v[226:227], off
	v_lshl_add_u64 v[226:227], v[224:225], 0, s[64:65]
	s_add_i32 m0, s13, 0x2000
	s_add_i32 s13, s15, s22
	ds_read_b128 v[178:181], v251 offset:51200
	ds_read_b128 v[182:185], v251 offset:52224
	global_load_lds_dwordx4 v[226:227], off
	v_lshl_add_u64 v[226:227], v[224:225], 0, s[66:67]
	s_mov_b32 m0, s13
	v_lshl_add_u64 v[224:225], v[224:225], 0, s[68:69]
	ds_read_b128 v[186:189], v251 offset:53248
	ds_read_b128 v[190:193], v251 offset:54272
	global_load_lds_dwordx4 v[226:227], off
	s_add_i32 m0, s13, 0x2000
	s_nop 0
	ds_read_b128 v[216:219], v251 offset:55296
	ds_read_b128 v[220:223], v251 offset:56320
	global_load_lds_dwordx4 v[224:225], off
	v_lshl_add_u64 v[224:225], v[206:207], 0, s[62:63]
	s_mov_b32 m0, s27
	v_lshl_add_u64 v[206:207], v[206:207], 0, s[66:67]
	global_load_lds_dwordx4 v[224:225], off
	s_mov_b32 m0, s28
	s_nop 0
	global_load_lds_dwordx4 v[206:207], off
	s_waitcnt vmcnt(8)
	s_waitcnt lgkmcnt(0)
	s_barrier
	s_setprio 1
	s_waitcnt lgkmcnt(0)
	v_mfma_f32_16x16x32_bf16 v[62:65], v[138:141], v[170:173], v[62:65]
	v_mfma_f32_16x16x32_bf16 v[58:61], v[146:149], v[170:173], v[58:61]
	v_mfma_f32_16x16x32_bf16 v[46:49], v[138:141], v[178:181], v[46:49]
	v_mfma_f32_16x16x32_bf16 v[42:45], v[146:149], v[178:181], v[42:45]
	v_mfma_f32_16x16x32_bf16 v[30:33], v[138:141], v[186:189], v[30:33]
	v_mfma_f32_16x16x32_bf16 v[26:29], v[146:149], v[186:189], v[26:29]
	v_mfma_f32_16x16x32_bf16 v[14:17], v[138:141], v[216:219], v[14:17]
	v_mfma_f32_16x16x32_bf16 v[10:13], v[146:149], v[216:219], v[10:13]
	v_mfma_f32_16x16x32_bf16 v[62:65], v[142:145], v[174:177], v[62:65]
	v_mfma_f32_16x16x32_bf16 v[58:61], v[150:153], v[174:177], v[58:61]
	v_mfma_f32_16x16x32_bf16 v[46:49], v[142:145], v[182:185], v[46:49]
	v_mfma_f32_16x16x32_bf16 v[42:45], v[150:153], v[182:185], v[42:45]
	v_mfma_f32_16x16x32_bf16 v[30:33], v[142:145], v[190:193], v[30:33]
	v_mfma_f32_16x16x32_bf16 v[26:29], v[150:153], v[190:193], v[26:29]
	v_mfma_f32_16x16x32_bf16 v[14:17], v[142:145], v[220:223], v[14:17]
	v_mfma_f32_16x16x32_bf16 v[10:13], v[150:153], v[220:223], v[10:13]
	s_setprio 0
	s_setprio 1
	v_mfma_f32_16x16x32_bf16 v[54:57], v[154:157], v[170:173], v[54:57]
	v_mfma_f32_16x16x32_bf16 v[50:53], v[162:165], v[170:173], v[50:53]
	v_mfma_f32_16x16x32_bf16 v[38:41], v[154:157], v[178:181], v[38:41]
	v_mfma_f32_16x16x32_bf16 v[34:37], v[162:165], v[178:181], v[34:37]
	v_mfma_f32_16x16x32_bf16 v[22:25], v[154:157], v[186:189], v[22:25]
	v_mfma_f32_16x16x32_bf16 v[18:21], v[162:165], v[186:189], v[18:21]
	v_mfma_f32_16x16x32_bf16 v[6:9], v[154:157], v[216:219], v[6:9]
	v_mfma_f32_16x16x32_bf16 v[2:5], v[162:165], v[216:219], v[2:5]
	v_mfma_f32_16x16x32_bf16 v[54:57], v[158:161], v[174:177], v[54:57]
	v_mfma_f32_16x16x32_bf16 v[50:53], v[166:169], v[174:177], v[50:53]
	v_mfma_f32_16x16x32_bf16 v[38:41], v[158:161], v[182:185], v[38:41]
	v_mfma_f32_16x16x32_bf16 v[34:37], v[166:169], v[182:185], v[34:37]
	v_mfma_f32_16x16x32_bf16 v[22:25], v[158:161], v[190:193], v[22:25]
	v_mfma_f32_16x16x32_bf16 v[18:21], v[166:169], v[190:193], v[18:21]
	v_mfma_f32_16x16x32_bf16 v[6:9], v[158:161], v[220:223], v[6:9]
	v_mfma_f32_16x16x32_bf16 v[2:5], v[166:169], v[220:223], v[2:5]
	s_setprio 0
	s_barrier
	s_add_i32 s11, s11, 2
	v_lshl_add_u64 v[134:135], v[134:135], 0, s[72:73]
	s_cmp_gt_u32 s11, 29
	v_lshl_add_u64 v[130:131], v[130:131], 0, s[72:73]
	s_cbranch_scc0 .LBB0_420
	s_and_b64 vcc, exec, s[2:3]
	s_cbranch_vccz .LBB0_423
	s_barrier

.LBB0_505:
	s_add_i32 s9, 0, 0x10000
	s_add_i32 s13, 0, 0x14000
	v_lshl_add_u64 v[168:169], v[152:153], 0, s[74:75]
	v_add_u32_e32 v180, s9, v162
	v_add_u32_e32 v196, s13, v162
	v_cndmask_b32_e32 v205, v169, v155, vcc
	v_cndmask_b32_e32 v204, v168, v0, vcc
	ds_read_b128 v[168:171], v180
	ds_read_b128 v[172:175], v180 offset:1024
	ds_read_b128 v[176:179], v180 offset:2048
	ds_read_b128 v[180:183], v180 offset:3072
	ds_read_b128 v[184:187], v196
	ds_read_b128 v[188:191], v196 offset:1024
	ds_read_b128 v[192:195], v196 offset:2048
	ds_read_b128 v[196:199], v196 offset:3072
	v_cndmask_b32_e32 v239, v151, v157, vcc
	v_cndmask_b32_e32 v238, v150, v154, vcc
	v_lshl_add_u64 v[250:251], v[152:153], 0, v[144:145]
	s_add_i32 m0, s21, 0xc000
	ds_read_b128 v[200:203], v166
	ds_read_b128 v[210:213], v166 offset:1024
	ds_read_b128 v[214:217], v166 offset:2048
	ds_read_b128 v[218:221], v166 offset:3072
	ds_read_b128 v[222:225], v166 offset:4096
	ds_read_b128 v[226:229], v166 offset:5120
	ds_read_b128 v[230:233], v166 offset:6144
	ds_read_b128 v[234:237], v166 offset:7168
	global_load_lds_dwordx4 v[250:251], off
	v_lshl_add_u64 v[250:251], v[250:251], 0, s[52:53]
	s_add_i32 m0, s21, 0xe000
	s_nop 0
	global_load_lds_dwordx4 v[250:251], off
	s_waitcnt vmcnt(8)
	s_waitcnt lgkmcnt(0)
	s_barrier
	s_setprio 1
	s_waitcnt lgkmcnt(0)
	v_mfma_f32_16x16x32_bf16 v[126:129], v[168:171], v[200:203], v[126:129]
	v_mfma_f32_16x16x32_bf16 v[122:125], v[176:179], v[200:203], v[122:125]
	v_mfma_f32_16x16x32_bf16 v[110:113], v[168:171], v[214:217], v[110:113]
	v_mfma_f32_16x16x32_bf16 v[106:109], v[176:179], v[214:217], v[106:109]
	v_mfma_f32_16x16x32_bf16 v[94:97], v[168:171], v[222:225], v[94:97]
	v_mfma_f32_16x16x32_bf16 v[90:93], v[176:179], v[222:225], v[90:93]
	v_mfma_f32_16x16x32_bf16 v[78:81], v[168:171], v[230:233], v[78:81]
	v_mfma_f32_16x16x32_bf16 v[74:77], v[176:179], v[230:233], v[74:77]
	v_mfma_f32_16x16x32_bf16 v[126:129], v[172:175], v[210:213], v[126:129]
	v_mfma_f32_16x16x32_bf16 v[122:125], v[180:183], v[210:213], v[122:125]
	v_mfma_f32_16x16x32_bf16 v[110:113], v[172:175], v[218:221], v[110:113]
	v_mfma_f32_16x16x32_bf16 v[106:109], v[180:183], v[218:221], v[106:109]
	v_mfma_f32_16x16x32_bf16 v[94:97], v[172:175], v[226:229], v[94:97]
	v_mfma_f32_16x16x32_bf16 v[90:93], v[180:183], v[226:229], v[90:93]
	v_mfma_f32_16x16x32_bf16 v[78:81], v[172:175], v[234:237], v[78:81]
	v_mfma_f32_16x16x32_bf16 v[74:77], v[180:183], v[234:237], v[74:77]
	s_setprio 0
	s_setprio 1
	v_mfma_f32_16x16x32_bf16 v[118:121], v[184:187], v[200:203], v[118:121]
	v_mfma_f32_16x16x32_bf16 v[114:117], v[192:195], v[200:203], v[114:117]
	v_mfma_f32_16x16x32_bf16 v[102:105], v[184:187], v[214:217], v[102:105]
	v_mfma_f32_16x16x32_bf16 v[98:101], v[192:195], v[214:217], v[98:101]
	v_mfma_f32_16x16x32_bf16 v[86:89], v[184:187], v[222:225], v[86:89]
	v_mfma_f32_16x16x32_bf16 v[82:85], v[192:195], v[222:225], v[82:85]
	v_mfma_f32_16x16x32_bf16 v[70:73], v[184:187], v[230:233], v[70:73]
	v_mfma_f32_16x16x32_bf16 v[66:69], v[192:195], v[230:233], v[66:69]
	v_mfma_f32_16x16x32_bf16 v[118:121], v[188:191], v[210:213], v[118:121]
	v_mfma_f32_16x16x32_bf16 v[114:117], v[196:199], v[210:213], v[114:117]
	v_mfma_f32_16x16x32_bf16 v[102:105], v[188:191], v[218:221], v[102:105]
	v_mfma_f32_16x16x32_bf16 v[98:101], v[196:199], v[218:221], v[98:101]
	v_mfma_f32_16x16x32_bf16 v[86:89], v[188:191], v[226:229], v[86:89]
	v_mfma_f32_16x16x32_bf16 v[82:85], v[196:199], v[226:229], v[82:85]
	v_mfma_f32_16x16x32_bf16 v[70:73], v[188:191], v[234:237], v[70:73]
	v_mfma_f32_16x16x32_bf16 v[66:69], v[196:199], v[234:237], v[66:69]
	s_setprio 0
	s_barrier
	s_add_i32 s9, s9, s20
	v_lshl_add_u64 v[238:239], v[238:239], 0, v[136:137]
	s_mov_b32 m0, s9
	ds_read_b128 v[200:203], v166 offset:16384
	ds_read_b128 v[210:213], v166 offset:17408
	global_load_lds_dwordx4 v[238:239], off
	v_lshl_add_u64 v[250:251], v[238:239], 0, s[52:53]
	s_add_i32 m0, s9, 0x2000
	s_add_i32 s9, s13, s20
	ds_read_b128 v[214:217], v166 offset:18432
	ds_read_b128 v[218:221], v166 offset:19456
	global_load_lds_dwordx4 v[250:251], off
	v_lshl_add_u64 v[250:251], v[238:239], 0, s[54:55]
	s_mov_b32 m0, s9
	v_lshl_add_u64 v[204:205], v[204:205], 0, v[134:135]
	ds_read_b128 v[222:225], v166 offset:20480
	ds_read_b128 v[226:229], v166 offset:21504
	global_load_lds_dwordx4 v[250:251], off
	v_lshl_add_u64 v[250:251], v[238:239], 0, s[56:57]
	s_add_i32 m0, s9, 0x2000
	s_nop 0
	ds_read_b128 v[230:233], v166 offset:22528
	ds_read_b128 v[234:237], v166 offset:23552
	global_load_lds_dwordx4 v[250:251], off
	s_mov_b32 m0, s21
	v_lshl_add_u64 v[250:251], v[204:205], 0, s[52:53]
	global_load_lds_dwordx4 v[204:205], off
	s_mov_b32 m0, s22
	s_nop 0
	global_load_lds_dwordx4 v[250:251], off
	s_waitcnt vmcnt(8)
	s_waitcnt lgkmcnt(0)
	s_barrier
	s_setprio 1
	s_waitcnt lgkmcnt(0)
	v_mfma_f32_16x16x32_bf16 v[62:65], v[168:171], v[200:203], v[62:65]
	v_mfma_f32_16x16x32_bf16 v[58:61], v[176:179], v[200:203], v[58:61]
	v_mfma_f32_16x16x32_bf16 v[46:49], v[168:171], v[214:217], v[46:49]
	v_mfma_f32_16x16x32_bf16 v[42:45], v[176:179], v[214:217], v[42:45]
	v_mfma_f32_16x16x32_bf16 v[30:33], v[168:171], v[222:225], v[30:33]
	v_mfma_f32_16x16x32_bf16 v[26:29], v[176:179], v[222:225], v[26:29]
	v_mfma_f32_16x16x32_bf16 v[10:13], v[168:171], v[230:233], v[10:13]
	v_mfma_f32_16x16x32_bf16 v[6:9], v[176:179], v[230:233], v[6:9]
	v_mfma_f32_16x16x32_bf16 v[62:65], v[172:175], v[210:213], v[62:65]
	v_mfma_f32_16x16x32_bf16 v[58:61], v[180:183], v[210:213], v[58:61]
	v_mfma_f32_16x16x32_bf16 v[46:49], v[172:175], v[218:221], v[46:49]
	v_mfma_f32_16x16x32_bf16 v[42:45], v[180:183], v[218:221], v[42:45]
	v_mfma_f32_16x16x32_bf16 v[30:33], v[172:175], v[226:229], v[30:33]
	v_mfma_f32_16x16x32_bf16 v[26:29], v[180:183], v[226:229], v[26:29]
	v_mfma_f32_16x16x32_bf16 v[10:13], v[172:175], v[234:237], v[10:13]
	v_mfma_f32_16x16x32_bf16 v[6:9], v[180:183], v[234:237], v[6:9]
	s_setprio 0
	s_setprio 1
	v_mfma_f32_16x16x32_bf16 v[54:57], v[184:187], v[200:203], v[54:57]
	v_mfma_f32_16x16x32_bf16 v[50:53], v[192:195], v[200:203], v[50:53]
	v_mfma_f32_16x16x32_bf16 v[38:41], v[184:187], v[214:217], v[38:41]
	v_mfma_f32_16x16x32_bf16 v[34:37], v[192:195], v[214:217], v[34:37]
	v_mfma_f32_16x16x32_bf16 v[22:25], v[184:187], v[222:225], v[22:25]
	v_mfma_f32_16x16x32_bf16 v[18:21], v[192:195], v[222:225], v[18:21]
	v_mfma_f32_16x16x32_bf16 v[2:5], v[184:187], v[230:233], v[2:5]
	v_mfma_f32_16x16x32_bf16 v[14:17], v[192:195], v[230:233], v[14:17]
	v_mfma_f32_16x16x32_bf16 v[54:57], v[188:191], v[210:213], v[54:57]
	v_mfma_f32_16x16x32_bf16 v[50:53], v[196:199], v[210:213], v[50:53]
	v_mfma_f32_16x16x32_bf16 v[38:41], v[188:191], v[218:221], v[38:41]
	v_mfma_f32_16x16x32_bf16 v[34:37], v[196:199], v[218:221], v[34:37]
	v_mfma_f32_16x16x32_bf16 v[22:25], v[188:191], v[226:229], v[22:25]
	v_mfma_f32_16x16x32_bf16 v[18:21], v[196:199], v[226:229], v[18:21]
	v_mfma_f32_16x16x32_bf16 v[2:5], v[188:191], v[234:237], v[2:5]
	v_mfma_f32_16x16x32_bf16 v[14:17], v[196:199], v[234:237], v[14:17]
	s_setprio 0
	s_barrier
	s_add_i32 s9, 0, 0x18000
	s_add_i32 s13, 0, 0x1c000
	v_add_u32_e32 v180, s9, v162
	v_add_u32_e32 v196, s13, v162
	ds_read_b128 v[168:171], v180
	ds_read_b128 v[172:175], v180 offset:1024
	ds_read_b128 v[176:179], v180 offset:2048
	ds_read_b128 v[180:183], v180 offset:3072
	ds_read_b128 v[184:187], v196
	ds_read_b128 v[188:191], v196 offset:1024
	ds_read_b128 v[192:195], v196 offset:2048
	ds_read_b128 v[196:199], v196 offset:3072
	s_mov_b32 m0, s23
	v_lshl_add_u64 v[250:251], v[204:205], 0, s[54:55]
	ds_read_b128 v[200:203], v166 offset:32768
	ds_read_b128 v[210:213], v166 offset:33792
	ds_read_b128 v[214:217], v166 offset:34816
	ds_read_b128 v[218:221], v166 offset:35840
	ds_read_b128 v[222:225], v166 offset:36864
	ds_read_b128 v[226:229], v166 offset:37888
	ds_read_b128 v[230:233], v166 offset:38912
	ds_read_b128 v[234:237], v166 offset:39936
	global_load_lds_dwordx4 v[250:251], off
	v_lshl_add_u64 v[250:251], v[204:205], 0, s[56:57]
	s_mov_b32 m0, s24
	s_nop 0
	global_load_lds_dwordx4 v[250:251], off
	s_waitcnt vmcnt(8)
	s_waitcnt lgkmcnt(0)
	s_barrier
	s_setprio 1
	s_waitcnt lgkmcnt(0)
	v_mfma_f32_16x16x32_bf16 v[126:129], v[168:171], v[200:203], v[126:129]
	v_mfma_f32_16x16x32_bf16 v[122:125], v[176:179], v[200:203], v[122:125]
	v_mfma_f32_16x16x32_bf16 v[110:113], v[168:171], v[214:217], v[110:113]
	v_mfma_f32_16x16x32_bf16 v[106:109], v[176:179], v[214:217], v[106:109]
	v_mfma_f32_16x16x32_bf16 v[94:97], v[168:171], v[222:225], v[94:97]
	v_mfma_f32_16x16x32_bf16 v[90:93], v[176:179], v[222:225], v[90:93]
	v_mfma_f32_16x16x32_bf16 v[78:81], v[168:171], v[230:233], v[78:81]
	v_mfma_f32_16x16x32_bf16 v[74:77], v[176:179], v[230:233], v[74:77]
	v_mfma_f32_16x16x32_bf16 v[126:129], v[172:175], v[210:213], v[126:129]
	v_mfma_f32_16x16x32_bf16 v[122:125], v[180:183], v[210:213], v[122:125]
	v_mfma_f32_16x16x32_bf16 v[110:113], v[172:175], v[218:221], v[110:113]
	v_mfma_f32_16x16x32_bf16 v[106:109], v[180:183], v[218:221], v[106:109]
	v_mfma_f32_16x16x32_bf16 v[94:97], v[172:175], v[226:229], v[94:97]
	v_mfma_f32_16x16x32_bf16 v[90:93], v[180:183], v[226:229], v[90:93]
	v_mfma_f32_16x16x32_bf16 v[78:81], v[172:175], v[234:237], v[78:81]
	v_mfma_f32_16x16x32_bf16 v[74:77], v[180:183], v[234:237], v[74:77]
	s_setprio 0
	s_setprio 1
	v_mfma_f32_16x16x32_bf16 v[118:121], v[184:187], v[200:203], v[118:121]
	v_mfma_f32_16x16x32_bf16 v[114:117], v[192:195], v[200:203], v[114:117]
	v_mfma_f32_16x16x32_bf16 v[102:105], v[184:187], v[214:217], v[102:105]
	v_mfma_f32_16x16x32_bf16 v[98:101], v[192:195], v[214:217], v[98:101]
	v_mfma_f32_16x16x32_bf16 v[86:89], v[184:187], v[222:225], v[86:89]
	v_mfma_f32_16x16x32_bf16 v[82:85], v[192:195], v[222:225], v[82:85]
	v_mfma_f32_16x16x32_bf16 v[70:73], v[184:187], v[230:233], v[70:73]
	v_mfma_f32_16x16x32_bf16 v[66:69], v[192:195], v[230:233], v[66:69]
	v_mfma_f32_16x16x32_bf16 v[118:121], v[188:191], v[210:213], v[118:121]
	v_mfma_f32_16x16x32_bf16 v[114:117], v[196:199], v[210:213], v[114:117]
	v_mfma_f32_16x16x32_bf16 v[102:105], v[188:191], v[218:221], v[102:105]
	v_mfma_f32_16x16x32_bf16 v[98:101], v[196:199], v[218:221], v[98:101]
	v_mfma_f32_16x16x32_bf16 v[86:89], v[188:191], v[226:229], v[86:89]
	v_mfma_f32_16x16x32_bf16 v[82:85], v[196:199], v[226:229], v[82:85]
	v_mfma_f32_16x16x32_bf16 v[70:73], v[188:191], v[234:237], v[70:73]
	v_mfma_f32_16x16x32_bf16 v[66:69], v[196:199], v[234:237], v[66:69]
	s_setprio 0
	s_barrier
	s_add_i32 s9, s9, s20
	v_lshl_add_u64 v[250:251], v[238:239], 0, s[62:63]
	s_mov_b32 m0, s9
	ds_read_b128 v[200:203], v166 offset:49152
	ds_read_b128 v[210:213], v166 offset:50176
	global_load_lds_dwordx4 v[250:251], off
	v_lshl_add_u64 v[250:251], v[238:239], 0, s[64:65]
	s_add_i32 m0, s9, 0x2000
	s_add_i32 s9, s13, s20
	ds_read_b128 v[214:217], v166 offset:51200
	ds_read_b128 v[218:221], v166 offset:52224
	global_load_lds_dwordx4 v[250:251], off
	v_lshl_add_u64 v[250:251], v[238:239], 0, s[66:67]
	s_mov_b32 m0, s9
	v_lshl_add_u64 v[238:239], v[238:239], 0, s[68:69]
	ds_read_b128 v[222:225], v166 offset:53248
	ds_read_b128 v[226:229], v166 offset:54272
	global_load_lds_dwordx4 v[250:251], off
	s_add_i32 m0, s9, 0x2000
	s_nop 0
	ds_read_b128 v[230:233], v166 offset:55296
	ds_read_b128 v[234:237], v166 offset:56320
	global_load_lds_dwordx4 v[238:239], off
	v_lshl_add_u64 v[238:239], v[204:205], 0, s[62:63]
	s_mov_b32 m0, s25
	v_lshl_add_u64 v[204:205], v[204:205], 0, s[64:65]
	global_load_lds_dwordx4 v[238:239], off
	s_mov_b32 m0, s26
	s_nop 0
	global_load_lds_dwordx4 v[204:205], off
	s_waitcnt vmcnt(8)
	s_waitcnt lgkmcnt(0)
	s_barrier
	s_setprio 1
	s_waitcnt lgkmcnt(0)
	v_mfma_f32_16x16x32_bf16 v[62:65], v[168:171], v[200:203], v[62:65]
	v_mfma_f32_16x16x32_bf16 v[58:61], v[176:179], v[200:203], v[58:61]
	v_mfma_f32_16x16x32_bf16 v[46:49], v[168:171], v[214:217], v[46:49]
	v_mfma_f32_16x16x32_bf16 v[42:45], v[176:179], v[214:217], v[42:45]
	v_mfma_f32_16x16x32_bf16 v[30:33], v[168:171], v[222:225], v[30:33]
	v_mfma_f32_16x16x32_bf16 v[26:29], v[176:179], v[222:225], v[26:29]
	v_mfma_f32_16x16x32_bf16 v[10:13], v[168:171], v[230:233], v[10:13]
	v_mfma_f32_16x16x32_bf16 v[6:9], v[176:179], v[230:233], v[6:9]
	v_mfma_f32_16x16x32_bf16 v[62:65], v[172:175], v[210:213], v[62:65]
	v_mfma_f32_16x16x32_bf16 v[58:61], v[180:183], v[210:213], v[58:61]
	v_mfma_f32_16x16x32_bf16 v[46:49], v[172:175], v[218:221], v[46:49]
	v_mfma_f32_16x16x32_bf16 v[42:45], v[180:183], v[218:221], v[42:45]
	v_mfma_f32_16x16x32_bf16 v[30:33], v[172:175], v[226:229], v[30:33]
	v_mfma_f32_16x16x32_bf16 v[26:29], v[180:183], v[226:229], v[26:29]
	v_mfma_f32_16x16x32_bf16 v[10:13], v[172:175], v[234:237], v[10:13]
	v_mfma_f32_16x16x32_bf16 v[6:9], v[180:183], v[234:237], v[6:9]
	s_setprio 0
	s_setprio 1
	v_mfma_f32_16x16x32_bf16 v[54:57], v[184:187], v[200:203], v[54:57]
	v_mfma_f32_16x16x32_bf16 v[50:53], v[192:195], v[200:203], v[50:53]
	v_mfma_f32_16x16x32_bf16 v[38:41], v[184:187], v[214:217], v[38:41]
	v_mfma_f32_16x16x32_bf16 v[34:37], v[192:195], v[214:217], v[34:37]
	v_mfma_f32_16x16x32_bf16 v[22:25], v[184:187], v[222:225], v[22:25]
	v_mfma_f32_16x16x32_bf16 v[18:21], v[192:195], v[222:225], v[18:21]
	v_mfma_f32_16x16x32_bf16 v[2:5], v[184:187], v[230:233], v[2:5]
	v_mfma_f32_16x16x32_bf16 v[14:17], v[192:195], v[230:233], v[14:17]
	v_mfma_f32_16x16x32_bf16 v[54:57], v[188:191], v[210:213], v[54:57]
	v_mfma_f32_16x16x32_bf16 v[50:53], v[196:199], v[210:213], v[50:53]
	v_mfma_f32_16x16x32_bf16 v[38:41], v[188:191], v[218:221], v[38:41]
	v_mfma_f32_16x16x32_bf16 v[34:37], v[196:199], v[218:221], v[34:37]
	v_mfma_f32_16x16x32_bf16 v[22:25], v[188:191], v[226:229], v[22:25]
	v_mfma_f32_16x16x32_bf16 v[18:21], v[196:199], v[226:229], v[18:21]
	v_mfma_f32_16x16x32_bf16 v[2:5], v[188:191], v[234:237], v[2:5]
	v_mfma_f32_16x16x32_bf16 v[14:17], v[196:199], v[234:237], v[14:17]
	s_setprio 0
	s_barrier
	s_add_i32 s8, s8, 2
	v_lshl_add_u64 v[152:153], v[152:153], 0, s[72:73]
	s_cmp_gt_u32 s8, 29
	v_lshl_add_u64 v[150:151], v[150:151], 0, s[72:73]
	s_cbranch_scc1 .LBB0_508

.LBB0_1083:
	s_cmp_eq_u32 s8, 28
	s_cselect_b64 vcc, -1, 0
	s_add_i32 s9, 0, 0x10000
	v_add_u32_e32 v134, s9, v239
	s_add_i32 s11, 0, 0x14000
	ds_read_b128 v[136:139], v134
	ds_read_b128 v[140:143], v134 offset:1024
	ds_read_b128 v[144:147], v134 offset:2048
	ds_read_b128 v[148:151], v134 offset:3072
	v_add_u32_e32 v134, s11, v239
	ds_read_b128 v[152:155], v134
	ds_read_b128 v[156:159], v134 offset:1024
	ds_read_b128 v[160:163], v134 offset:2048
	ds_read_b128 v[164:167], v134 offset:3072
	s_mov_b32 s30, 0xfff40080
	s_mov_b32 s31, -1
	v_lshl_add_u64 v[168:169], v[132:133], 0, s[30:31]
	v_cndmask_b32_e32 v193, v169, v213, vcc
	v_cndmask_b32_e32 v192, v168, v212, vcc
	v_cndmask_b32_e32 v225, v131, v135, vcc
	v_cndmask_b32_e32 v224, v130, v0, vcc
	v_lshl_add_u64 v[226:227], v[132:133], 0, v[210:211]
	s_add_i32 m0, s17, 0xc000
	ds_read_b128 v[168:171], v251
	ds_read_b128 v[172:175], v251 offset:1024
	ds_read_b128 v[176:179], v251 offset:2048
	ds_read_b128 v[180:183], v251 offset:3072
	ds_read_b128 v[184:187], v251 offset:4096
	ds_read_b128 v[188:191], v251 offset:5120
	ds_read_b128 v[216:219], v251 offset:6144
	ds_read_b128 v[220:223], v251 offset:7168
	global_load_lds_dwordx4 v[226:227], off
	v_lshl_add_u64 v[226:227], v[226:227], 0, s[90:91]
	s_add_i32 m0, s17, 0xe000
	s_nop 0
	global_load_lds_dwordx4 v[226:227], off
	s_waitcnt vmcnt(8)
	s_waitcnt lgkmcnt(0)
	s_barrier
	s_setprio 1
	s_waitcnt lgkmcnt(0)
	v_mfma_f32_16x16x32_bf16 v[122:125], v[136:139], v[168:171], v[122:125]
	v_mfma_f32_16x16x32_bf16 v[126:129], v[144:147], v[168:171], v[126:129]
	v_mfma_f32_16x16x32_bf16 v[110:113], v[136:139], v[176:179], v[110:113]
	v_mfma_f32_16x16x32_bf16 v[106:109], v[144:147], v[176:179], v[106:109]
	v_mfma_f32_16x16x32_bf16 v[94:97], v[136:139], v[184:187], v[94:97]
	v_mfma_f32_16x16x32_bf16 v[90:93], v[144:147], v[184:187], v[90:93]
	v_mfma_f32_16x16x32_bf16 v[78:81], v[136:139], v[216:219], v[78:81]
	v_mfma_f32_16x16x32_bf16 v[74:77], v[144:147], v[216:219], v[74:77]
	v_mfma_f32_16x16x32_bf16 v[122:125], v[140:143], v[172:175], v[122:125]
	v_mfma_f32_16x16x32_bf16 v[126:129], v[148:151], v[172:175], v[126:129]
	v_mfma_f32_16x16x32_bf16 v[110:113], v[140:143], v[180:183], v[110:113]
	v_mfma_f32_16x16x32_bf16 v[106:109], v[148:151], v[180:183], v[106:109]
	v_mfma_f32_16x16x32_bf16 v[94:97], v[140:143], v[188:191], v[94:97]
	v_mfma_f32_16x16x32_bf16 v[90:93], v[148:151], v[188:191], v[90:93]
	v_mfma_f32_16x16x32_bf16 v[78:81], v[140:143], v[220:223], v[78:81]
	v_mfma_f32_16x16x32_bf16 v[74:77], v[148:151], v[220:223], v[74:77]
	s_setprio 0
	s_setprio 1
	v_mfma_f32_16x16x32_bf16 v[118:121], v[152:155], v[168:171], v[118:121]
	v_mfma_f32_16x16x32_bf16 v[114:117], v[160:163], v[168:171], v[114:117]
	v_mfma_f32_16x16x32_bf16 v[102:105], v[152:155], v[176:179], v[102:105]
	v_mfma_f32_16x16x32_bf16 v[98:101], v[160:163], v[176:179], v[98:101]
	v_mfma_f32_16x16x32_bf16 v[86:89], v[152:155], v[184:187], v[86:89]
	v_mfma_f32_16x16x32_bf16 v[82:85], v[160:163], v[184:187], v[82:85]
	v_mfma_f32_16x16x32_bf16 v[70:73], v[152:155], v[216:219], v[70:73]
	v_mfma_f32_16x16x32_bf16 v[66:69], v[160:163], v[216:219], v[66:69]
	v_mfma_f32_16x16x32_bf16 v[118:121], v[156:159], v[172:175], v[118:121]
	v_mfma_f32_16x16x32_bf16 v[114:117], v[164:167], v[172:175], v[114:117]
	v_mfma_f32_16x16x32_bf16 v[102:105], v[156:159], v[180:183], v[102:105]
	v_mfma_f32_16x16x32_bf16 v[98:101], v[164:167], v[180:183], v[98:101]
	v_mfma_f32_16x16x32_bf16 v[86:89], v[156:159], v[188:191], v[86:89]
	v_mfma_f32_16x16x32_bf16 v[82:85], v[164:167], v[188:191], v[82:85]
	v_mfma_f32_16x16x32_bf16 v[70:73], v[156:159], v[220:223], v[70:73]
	v_mfma_f32_16x16x32_bf16 v[66:69], v[164:167], v[220:223], v[66:69]
	s_setprio 0
	s_barrier
	s_add_i32 s9, s9, s16
	v_lshl_add_u64 v[224:225], v[224:225], 0, v[200:201]
	s_mov_b32 m0, s9
	ds_read_b128 v[168:171], v251 offset:16384
	ds_read_b128 v[172:175], v251 offset:17408
	global_load_lds_dwordx4 v[224:225], off
	v_lshl_add_u64 v[226:227], v[224:225], 0, s[52:53]
	s_add_i32 m0, s9, 0x2000
	s_add_i32 s9, s11, s16
	ds_read_b128 v[176:179], v251 offset:18432
	ds_read_b128 v[180:183], v251 offset:19456
	global_load_lds_dwordx4 v[226:227], off
	v_lshl_add_u64 v[226:227], v[224:225], 0, s[54:55]
	s_mov_b32 m0, s9
	v_lshl_add_u64 v[192:193], v[192:193], 0, v[198:199]
	ds_read_b128 v[184:187], v251 offset:20480
	ds_read_b128 v[188:191], v251 offset:21504
	global_load_lds_dwordx4 v[226:227], off
	v_lshl_add_u64 v[226:227], v[224:225], 0, s[56:57]
	s_add_i32 m0, s9, 0x2000
	s_nop 0
	ds_read_b128 v[216:219], v251 offset:22528
	ds_read_b128 v[220:223], v251 offset:23552
	global_load_lds_dwordx4 v[226:227], off
	s_mov_b32 m0, s17
	v_lshl_add_u64 v[226:227], v[192:193], 0, s[90:91]
	global_load_lds_dwordx4 v[192:193], off
	s_mov_b32 m0, s18
	s_nop 0
	global_load_lds_dwordx4 v[226:227], off
	s_waitcnt vmcnt(8)
	s_waitcnt lgkmcnt(0)
	s_barrier
	s_setprio 1
	s_waitcnt lgkmcnt(0)
	v_mfma_f32_16x16x32_bf16 v[62:65], v[136:139], v[168:171], v[62:65]
	v_mfma_f32_16x16x32_bf16 v[58:61], v[144:147], v[168:171], v[58:61]
	v_mfma_f32_16x16x32_bf16 v[46:49], v[136:139], v[176:179], v[46:49]
	v_mfma_f32_16x16x32_bf16 v[42:45], v[144:147], v[176:179], v[42:45]
	v_mfma_f32_16x16x32_bf16 v[30:33], v[136:139], v[184:187], v[30:33]
	v_mfma_f32_16x16x32_bf16 v[26:29], v[144:147], v[184:187], v[26:29]
	v_mfma_f32_16x16x32_bf16 v[14:17], v[136:139], v[216:219], v[14:17]
	v_mfma_f32_16x16x32_bf16 v[10:13], v[144:147], v[216:219], v[10:13]
	v_mfma_f32_16x16x32_bf16 v[62:65], v[140:143], v[172:175], v[62:65]
	v_mfma_f32_16x16x32_bf16 v[58:61], v[148:151], v[172:175], v[58:61]
	v_mfma_f32_16x16x32_bf16 v[46:49], v[140:143], v[180:183], v[46:49]
	v_mfma_f32_16x16x32_bf16 v[42:45], v[148:151], v[180:183], v[42:45]
	v_mfma_f32_16x16x32_bf16 v[30:33], v[140:143], v[188:191], v[30:33]
	v_mfma_f32_16x16x32_bf16 v[26:29], v[148:151], v[188:191], v[26:29]
	v_mfma_f32_16x16x32_bf16 v[14:17], v[140:143], v[220:223], v[14:17]
	v_mfma_f32_16x16x32_bf16 v[10:13], v[148:151], v[220:223], v[10:13]
	s_setprio 0
	s_setprio 1
	v_mfma_f32_16x16x32_bf16 v[54:57], v[152:155], v[168:171], v[54:57]
	v_mfma_f32_16x16x32_bf16 v[50:53], v[160:163], v[168:171], v[50:53]
	v_mfma_f32_16x16x32_bf16 v[38:41], v[152:155], v[176:179], v[38:41]
	v_mfma_f32_16x16x32_bf16 v[34:37], v[160:163], v[176:179], v[34:37]
	v_mfma_f32_16x16x32_bf16 v[22:25], v[152:155], v[184:187], v[22:25]
	v_mfma_f32_16x16x32_bf16 v[18:21], v[160:163], v[184:187], v[18:21]
	v_mfma_f32_16x16x32_bf16 v[6:9], v[152:155], v[216:219], v[6:9]
	v_mfma_f32_16x16x32_bf16 v[2:5], v[160:163], v[216:219], v[2:5]
	v_mfma_f32_16x16x32_bf16 v[54:57], v[156:159], v[172:175], v[54:57]
	v_mfma_f32_16x16x32_bf16 v[50:53], v[164:167], v[172:175], v[50:53]
	v_mfma_f32_16x16x32_bf16 v[38:41], v[156:159], v[180:183], v[38:41]
	v_mfma_f32_16x16x32_bf16 v[34:37], v[164:167], v[180:183], v[34:37]
	v_mfma_f32_16x16x32_bf16 v[22:25], v[156:159], v[188:191], v[22:25]
	v_mfma_f32_16x16x32_bf16 v[18:21], v[164:167], v[188:191], v[18:21]
	v_mfma_f32_16x16x32_bf16 v[6:9], v[156:159], v[220:223], v[6:9]
	v_mfma_f32_16x16x32_bf16 v[2:5], v[164:167], v[220:223], v[2:5]
	s_setprio 0
	s_barrier
	s_add_i32 s9, 0, 0x18000
	v_add_u32_e32 v134, s9, v239
	s_add_i32 s11, 0, 0x1c000
	ds_read_b128 v[136:139], v134
	ds_read_b128 v[140:143], v134 offset:1024
	ds_read_b128 v[144:147], v134 offset:2048
	ds_read_b128 v[148:151], v134 offset:3072
	v_add_u32_e32 v134, s11, v239
	ds_read_b128 v[152:155], v134
	ds_read_b128 v[156:159], v134 offset:1024
	ds_read_b128 v[160:163], v134 offset:2048
	ds_read_b128 v[164:167], v134 offset:3072
	s_mov_b32 m0, s19
	v_lshl_add_u64 v[226:227], v[192:193], 0, s[56:57]
	ds_read_b128 v[168:171], v251 offset:32768
	ds_read_b128 v[172:175], v251 offset:33792
	ds_read_b128 v[176:179], v251 offset:34816
	ds_read_b128 v[180:183], v251 offset:35840
	ds_read_b128 v[184:187], v251 offset:36864
	ds_read_b128 v[188:191], v251 offset:37888
	ds_read_b128 v[216:219], v251 offset:38912
	ds_read_b128 v[220:223], v251 offset:39936
	global_load_lds_dwordx4 v[226:227], off
	v_lshl_add_u64 v[226:227], v[192:193], 0, s[78:79]
	s_mov_b32 m0, s20
	s_nop 0
	global_load_lds_dwordx4 v[226:227], off
	s_waitcnt vmcnt(8)
	s_waitcnt lgkmcnt(0)
	s_barrier
	s_setprio 1
	s_waitcnt lgkmcnt(0)
	v_mfma_f32_16x16x32_bf16 v[122:125], v[136:139], v[168:171], v[122:125]
	v_mfma_f32_16x16x32_bf16 v[126:129], v[144:147], v[168:171], v[126:129]
	v_mfma_f32_16x16x32_bf16 v[110:113], v[136:139], v[176:179], v[110:113]
	v_mfma_f32_16x16x32_bf16 v[106:109], v[144:147], v[176:179], v[106:109]
	v_mfma_f32_16x16x32_bf16 v[94:97], v[136:139], v[184:187], v[94:97]
	v_mfma_f32_16x16x32_bf16 v[90:93], v[144:147], v[184:187], v[90:93]
	v_mfma_f32_16x16x32_bf16 v[78:81], v[136:139], v[216:219], v[78:81]
	v_mfma_f32_16x16x32_bf16 v[74:77], v[144:147], v[216:219], v[74:77]
	v_mfma_f32_16x16x32_bf16 v[122:125], v[140:143], v[172:175], v[122:125]
	v_mfma_f32_16x16x32_bf16 v[126:129], v[148:151], v[172:175], v[126:129]
	v_mfma_f32_16x16x32_bf16 v[110:113], v[140:143], v[180:183], v[110:113]
	v_mfma_f32_16x16x32_bf16 v[106:109], v[148:151], v[180:183], v[106:109]
	v_mfma_f32_16x16x32_bf16 v[94:97], v[140:143], v[188:191], v[94:97]
	v_mfma_f32_16x16x32_bf16 v[90:93], v[148:151], v[188:191], v[90:93]
	v_mfma_f32_16x16x32_bf16 v[78:81], v[140:143], v[220:223], v[78:81]
	v_mfma_f32_16x16x32_bf16 v[74:77], v[148:151], v[220:223], v[74:77]
	s_setprio 0
	s_setprio 1
	v_mfma_f32_16x16x32_bf16 v[118:121], v[152:155], v[168:171], v[118:121]
	v_mfma_f32_16x16x32_bf16 v[114:117], v[160:163], v[168:171], v[114:117]
	v_mfma_f32_16x16x32_bf16 v[102:105], v[152:155], v[176:179], v[102:105]
	v_mfma_f32_16x16x32_bf16 v[98:101], v[160:163], v[176:179], v[98:101]
	v_mfma_f32_16x16x32_bf16 v[86:89], v[152:155], v[184:187], v[86:89]
	v_mfma_f32_16x16x32_bf16 v[82:85], v[160:163], v[184:187], v[82:85]
	v_mfma_f32_16x16x32_bf16 v[70:73], v[152:155], v[216:219], v[70:73]
	v_mfma_f32_16x16x32_bf16 v[66:69], v[160:163], v[216:219], v[66:69]
	v_mfma_f32_16x16x32_bf16 v[118:121], v[156:159], v[172:175], v[118:121]
	v_mfma_f32_16x16x32_bf16 v[114:117], v[164:167], v[172:175], v[114:117]
	v_mfma_f32_16x16x32_bf16 v[102:105], v[156:159], v[180:183], v[102:105]
	v_mfma_f32_16x16x32_bf16 v[98:101], v[164:167], v[180:183], v[98:101]
	v_mfma_f32_16x16x32_bf16 v[86:89], v[156:159], v[188:191], v[86:89]
	v_mfma_f32_16x16x32_bf16 v[82:85], v[164:167], v[188:191], v[82:85]
	v_mfma_f32_16x16x32_bf16 v[70:73], v[156:159], v[220:223], v[70:73]
	v_mfma_f32_16x16x32_bf16 v[66:69], v[164:167], v[220:223], v[66:69]
	s_setprio 0
	s_barrier
	s_add_i32 s9, s9, s16
	v_lshl_add_u64 v[226:227], v[224:225], 0, s[62:63]
	s_mov_b32 m0, s9
	ds_read_b128 v[168:171], v251 offset:49152
	ds_read_b128 v[172:175], v251 offset:50176
	global_load_lds_dwordx4 v[226:227], off
	v_lshl_add_u64 v[226:227], v[224:225], 0, s[64:65]
	s_add_i32 m0, s9, 0x2000
	s_add_i32 s9, s11, s16
	ds_read_b128 v[176:179], v251 offset:51200
	ds_read_b128 v[180:183], v251 offset:52224
	global_load_lds_dwordx4 v[226:227], off
	v_lshl_add_u64 v[226:227], v[224:225], 0, s[66:67]
	s_mov_b32 m0, s9
	v_lshl_add_u64 v[224:225], v[224:225], 0, s[68:69]
	ds_read_b128 v[184:187], v251 offset:53248
	ds_read_b128 v[188:191], v251 offset:54272
	global_load_lds_dwordx4 v[226:227], off
	s_add_i32 m0, s9, 0x2000
	s_nop 0
	ds_read_b128 v[216:219], v251 offset:55296
	ds_read_b128 v[220:223], v251 offset:56320
	global_load_lds_dwordx4 v[224:225], off
	v_lshl_add_u64 v[224:225], v[192:193], 0, s[62:63]
	s_mov_b32 m0, s21
	v_lshl_add_u64 v[192:193], v[192:193], 0, s[58:59]
	global_load_lds_dwordx4 v[224:225], off
	s_mov_b32 m0, s22
	s_nop 0
	global_load_lds_dwordx4 v[192:193], off
	s_waitcnt vmcnt(8)
	s_waitcnt lgkmcnt(0)
	s_barrier
	s_setprio 1
	s_waitcnt lgkmcnt(0)
	v_mfma_f32_16x16x32_bf16 v[62:65], v[136:139], v[168:171], v[62:65]
	v_mfma_f32_16x16x32_bf16 v[58:61], v[144:147], v[168:171], v[58:61]
	v_mfma_f32_16x16x32_bf16 v[46:49], v[136:139], v[176:179], v[46:49]
	v_mfma_f32_16x16x32_bf16 v[42:45], v[144:147], v[176:179], v[42:45]
	v_mfma_f32_16x16x32_bf16 v[30:33], v[136:139], v[184:187], v[30:33]
	v_mfma_f32_16x16x32_bf16 v[26:29], v[144:147], v[184:187], v[26:29]
	v_mfma_f32_16x16x32_bf16 v[14:17], v[136:139], v[216:219], v[14:17]
	v_mfma_f32_16x16x32_bf16 v[10:13], v[144:147], v[216:219], v[10:13]
	v_mfma_f32_16x16x32_bf16 v[62:65], v[140:143], v[172:175], v[62:65]
	v_mfma_f32_16x16x32_bf16 v[58:61], v[148:151], v[172:175], v[58:61]
	v_mfma_f32_16x16x32_bf16 v[46:49], v[140:143], v[180:183], v[46:49]
	v_mfma_f32_16x16x32_bf16 v[42:45], v[148:151], v[180:183], v[42:45]
	v_mfma_f32_16x16x32_bf16 v[30:33], v[140:143], v[188:191], v[30:33]
	v_mfma_f32_16x16x32_bf16 v[26:29], v[148:151], v[188:191], v[26:29]
	v_mfma_f32_16x16x32_bf16 v[14:17], v[140:143], v[220:223], v[14:17]
	v_mfma_f32_16x16x32_bf16 v[10:13], v[148:151], v[220:223], v[10:13]
	s_setprio 0
	s_setprio 1
	v_mfma_f32_16x16x32_bf16 v[54:57], v[152:155], v[168:171], v[54:57]
	v_mfma_f32_16x16x32_bf16 v[50:53], v[160:163], v[168:171], v[50:53]
	v_mfma_f32_16x16x32_bf16 v[38:41], v[152:155], v[176:179], v[38:41]
	v_mfma_f32_16x16x32_bf16 v[34:37], v[160:163], v[176:179], v[34:37]
	v_mfma_f32_16x16x32_bf16 v[22:25], v[152:155], v[184:187], v[22:25]
	v_mfma_f32_16x16x32_bf16 v[18:21], v[160:163], v[184:187], v[18:21]
	v_mfma_f32_16x16x32_bf16 v[6:9], v[152:155], v[216:219], v[6:9]
	v_mfma_f32_16x16x32_bf16 v[2:5], v[160:163], v[216:219], v[2:5]
	v_mfma_f32_16x16x32_bf16 v[54:57], v[156:159], v[172:175], v[54:57]
	v_mfma_f32_16x16x32_bf16 v[50:53], v[164:167], v[172:175], v[50:53]
	v_mfma_f32_16x16x32_bf16 v[38:41], v[156:159], v[180:183], v[38:41]
	v_mfma_f32_16x16x32_bf16 v[34:37], v[164:167], v[180:183], v[34:37]
	v_mfma_f32_16x16x32_bf16 v[22:25], v[156:159], v[188:191], v[22:25]
	v_mfma_f32_16x16x32_bf16 v[18:21], v[164:167], v[188:191], v[18:21]
	v_mfma_f32_16x16x32_bf16 v[6:9], v[156:159], v[220:223], v[6:9]
	v_mfma_f32_16x16x32_bf16 v[2:5], v[164:167], v[220:223], v[2:5]
	s_setprio 0
	s_barrier
	s_add_i32 s8, s8, 2
	v_lshl_add_u64 v[132:133], v[132:133], 0, s[72:73]
	s_cmp_gt_u32 s8, 29
	v_lshl_add_u64 v[130:131], v[130:131], 0, s[72:73]
	s_cbranch_scc0 .LBB0_1083
	s_and_b64 vcc, exec, s[2:3]
	s_cbranch_vccz .LBB0_1086
	s_barrier

.LBB0_1164:
	s_add_i32 s10, 0, 0x10000
	v_add_u32_e32 v154, s10, v163
	s_add_i32 s12, 0, 0x14000
	ds_read_b128 v[172:175], v154
	ds_read_b128 v[176:179], v154 offset:1024
	ds_read_b128 v[180:183], v154 offset:2048
	ds_read_b128 v[184:187], v154 offset:3072
	v_add_u32_e32 v154, s12, v163
	ds_read_b128 v[188:191], v154
	ds_read_b128 v[192:195], v154 offset:1024
	ds_read_b128 v[196:199], v154 offset:2048
	ds_read_b128 v[200:203], v154 offset:3072
	v_lshl_add_u64 v[164:165], v[150:151], 0, s[74:75]
	v_cndmask_b32_e32 v165, v165, v153, vcc
	v_cndmask_b32_e32 v164, v164, v0, vcc
	v_cndmask_b32_e32 v205, v149, v155, vcc
	v_cndmask_b32_e32 v204, v148, v152, vcc
	v_lshl_add_u64 v[206:207], v[150:151], 0, v[142:143]
	s_add_i32 m0, s18, 0xc000
	ds_read_b128 v[210:213], v169
	ds_read_b128 v[214:217], v169 offset:1024
	ds_read_b128 v[218:221], v169 offset:2048
	ds_read_b128 v[222:225], v169 offset:3072
	ds_read_b128 v[226:229], v169 offset:4096
	ds_read_b128 v[230:233], v169 offset:5120
	ds_read_b128 v[234:237], v169 offset:6144
	ds_read_b128 v[250:253], v169 offset:7168
	global_load_lds_dwordx4 v[206:207], off
	v_lshl_add_u64 v[206:207], v[206:207], 0, s[52:53]
	s_add_i32 m0, s18, 0xe000
	s_nop 0
	global_load_lds_dwordx4 v[206:207], off
	s_waitcnt vmcnt(8)
	s_waitcnt lgkmcnt(0)
	s_barrier
	s_setprio 1
	s_waitcnt lgkmcnt(0)
	v_mfma_f32_16x16x32_bf16 v[126:129], v[172:175], v[210:213], v[126:129]
	v_mfma_f32_16x16x32_bf16 v[122:125], v[180:183], v[210:213], v[122:125]
	v_mfma_f32_16x16x32_bf16 v[110:113], v[172:175], v[218:221], v[110:113]
	v_mfma_f32_16x16x32_bf16 v[106:109], v[180:183], v[218:221], v[106:109]
	v_mfma_f32_16x16x32_bf16 v[94:97], v[172:175], v[226:229], v[94:97]
	v_mfma_f32_16x16x32_bf16 v[90:93], v[180:183], v[226:229], v[90:93]
	v_mfma_f32_16x16x32_bf16 v[78:81], v[172:175], v[234:237], v[78:81]
	v_mfma_f32_16x16x32_bf16 v[74:77], v[180:183], v[234:237], v[74:77]
	v_mfma_f32_16x16x32_bf16 v[126:129], v[176:179], v[214:217], v[126:129]
	v_mfma_f32_16x16x32_bf16 v[122:125], v[184:187], v[214:217], v[122:125]
	v_mfma_f32_16x16x32_bf16 v[110:113], v[176:179], v[222:225], v[110:113]
	v_mfma_f32_16x16x32_bf16 v[106:109], v[184:187], v[222:225], v[106:109]
	v_mfma_f32_16x16x32_bf16 v[94:97], v[176:179], v[230:233], v[94:97]
	v_mfma_f32_16x16x32_bf16 v[90:93], v[184:187], v[230:233], v[90:93]
	v_mfma_f32_16x16x32_bf16 v[78:81], v[176:179], v[250:253], v[78:81]
	v_mfma_f32_16x16x32_bf16 v[74:77], v[184:187], v[250:253], v[74:77]
	s_setprio 0
	s_setprio 1
	v_mfma_f32_16x16x32_bf16 v[118:121], v[188:191], v[210:213], v[118:121]
	v_mfma_f32_16x16x32_bf16 v[114:117], v[196:199], v[210:213], v[114:117]
	v_mfma_f32_16x16x32_bf16 v[102:105], v[188:191], v[218:221], v[102:105]
	v_mfma_f32_16x16x32_bf16 v[98:101], v[196:199], v[218:221], v[98:101]
	v_mfma_f32_16x16x32_bf16 v[86:89], v[188:191], v[226:229], v[86:89]
	v_mfma_f32_16x16x32_bf16 v[82:85], v[196:199], v[226:229], v[82:85]
	v_mfma_f32_16x16x32_bf16 v[70:73], v[188:191], v[234:237], v[70:73]
	v_mfma_f32_16x16x32_bf16 v[66:69], v[196:199], v[234:237], v[66:69]
	v_mfma_f32_16x16x32_bf16 v[118:121], v[192:195], v[214:217], v[118:121]
	v_mfma_f32_16x16x32_bf16 v[114:117], v[200:203], v[214:217], v[114:117]
	v_mfma_f32_16x16x32_bf16 v[102:105], v[192:195], v[222:225], v[102:105]
	v_mfma_f32_16x16x32_bf16 v[98:101], v[200:203], v[222:225], v[98:101]
	v_mfma_f32_16x16x32_bf16 v[86:89], v[192:195], v[230:233], v[86:89]
	v_mfma_f32_16x16x32_bf16 v[82:85], v[200:203], v[230:233], v[82:85]
	v_mfma_f32_16x16x32_bf16 v[70:73], v[192:195], v[250:253], v[70:73]
	v_mfma_f32_16x16x32_bf16 v[66:69], v[200:203], v[250:253], v[66:69]
	s_setprio 0
	s_barrier
	s_add_i32 s10, s10, s16
	v_lshl_add_u64 v[204:205], v[204:205], 0, v[134:135]
	s_mov_b32 m0, s10
	ds_read_b128 v[210:213], v169 offset:16384
	ds_read_b128 v[214:217], v169 offset:17408
	global_load_lds_dwordx4 v[204:205], off
	v_lshl_add_u64 v[206:207], v[204:205], 0, s[52:53]
	s_add_i32 m0, s10, 0x2000
	s_add_i32 s10, s12, s16
	ds_read_b128 v[218:221], v169 offset:18432
	ds_read_b128 v[222:225], v169 offset:19456
	global_load_lds_dwordx4 v[206:207], off
	v_lshl_add_u64 v[206:207], v[204:205], 0, s[54:55]
	s_mov_b32 m0, s10
	v_lshl_add_u64 v[164:165], v[164:165], 0, v[136:137]
	ds_read_b128 v[226:229], v169 offset:20480
	ds_read_b128 v[230:233], v169 offset:21504
	global_load_lds_dwordx4 v[206:207], off
	v_lshl_add_u64 v[206:207], v[204:205], 0, s[56:57]
	s_add_i32 m0, s10, 0x2000
	s_nop 0
	ds_read_b128 v[234:237], v169 offset:22528
	ds_read_b128 v[250:253], v169 offset:23552
	global_load_lds_dwordx4 v[206:207], off
	s_mov_b32 m0, s18
	v_lshl_add_u64 v[206:207], v[164:165], 0, s[52:53]
	global_load_lds_dwordx4 v[164:165], off
	s_mov_b32 m0, s19
	s_nop 0
	global_load_lds_dwordx4 v[206:207], off
	s_waitcnt vmcnt(8)
	s_waitcnt lgkmcnt(0)
	s_barrier
	s_setprio 1
	s_waitcnt lgkmcnt(0)
	v_mfma_f32_16x16x32_bf16 v[62:65], v[172:175], v[210:213], v[62:65]
	v_mfma_f32_16x16x32_bf16 v[58:61], v[180:183], v[210:213], v[58:61]
	v_mfma_f32_16x16x32_bf16 v[46:49], v[172:175], v[218:221], v[46:49]
	v_mfma_f32_16x16x32_bf16 v[42:45], v[180:183], v[218:221], v[42:45]
	v_mfma_f32_16x16x32_bf16 v[30:33], v[172:175], v[226:229], v[30:33]
	v_mfma_f32_16x16x32_bf16 v[26:29], v[180:183], v[226:229], v[26:29]
	v_mfma_f32_16x16x32_bf16 v[14:17], v[172:175], v[234:237], v[14:17]
	v_mfma_f32_16x16x32_bf16 v[10:13], v[180:183], v[234:237], v[10:13]
	v_mfma_f32_16x16x32_bf16 v[62:65], v[176:179], v[214:217], v[62:65]
	v_mfma_f32_16x16x32_bf16 v[58:61], v[184:187], v[214:217], v[58:61]
	v_mfma_f32_16x16x32_bf16 v[46:49], v[176:179], v[222:225], v[46:49]
	v_mfma_f32_16x16x32_bf16 v[42:45], v[184:187], v[222:225], v[42:45]
	v_mfma_f32_16x16x32_bf16 v[30:33], v[176:179], v[230:233], v[30:33]
	v_mfma_f32_16x16x32_bf16 v[26:29], v[184:187], v[230:233], v[26:29]
	v_mfma_f32_16x16x32_bf16 v[14:17], v[176:179], v[250:253], v[14:17]
	v_mfma_f32_16x16x32_bf16 v[10:13], v[184:187], v[250:253], v[10:13]
	s_setprio 0
	s_setprio 1
	v_mfma_f32_16x16x32_bf16 v[54:57], v[188:191], v[210:213], v[54:57]
	v_mfma_f32_16x16x32_bf16 v[50:53], v[196:199], v[210:213], v[50:53]
	v_mfma_f32_16x16x32_bf16 v[38:41], v[188:191], v[218:221], v[38:41]
	v_mfma_f32_16x16x32_bf16 v[34:37], v[196:199], v[218:221], v[34:37]
	v_mfma_f32_16x16x32_bf16 v[22:25], v[188:191], v[226:229], v[22:25]
	v_mfma_f32_16x16x32_bf16 v[18:21], v[196:199], v[226:229], v[18:21]
	v_mfma_f32_16x16x32_bf16 v[2:5], v[188:191], v[234:237], v[2:5]
	v_mfma_f32_16x16x32_bf16 v[6:9], v[196:199], v[234:237], v[6:9]
	v_mfma_f32_16x16x32_bf16 v[54:57], v[192:195], v[214:217], v[54:57]
	v_mfma_f32_16x16x32_bf16 v[50:53], v[200:203], v[214:217], v[50:53]
	v_mfma_f32_16x16x32_bf16 v[38:41], v[192:195], v[222:225], v[38:41]
	v_mfma_f32_16x16x32_bf16 v[34:37], v[200:203], v[222:225], v[34:37]
	v_mfma_f32_16x16x32_bf16 v[22:25], v[192:195], v[230:233], v[22:25]
	v_mfma_f32_16x16x32_bf16 v[18:21], v[200:203], v[230:233], v[18:21]
	v_mfma_f32_16x16x32_bf16 v[2:5], v[192:195], v[250:253], v[2:5]
	v_mfma_f32_16x16x32_bf16 v[6:9], v[200:203], v[250:253], v[6:9]
	s_setprio 0
	s_barrier
	s_add_i32 s10, 0, 0x18000
	v_add_u32_e32 v154, s10, v163
	s_add_i32 s12, 0, 0x1c000
	ds_read_b128 v[172:175], v154
	ds_read_b128 v[176:179], v154 offset:1024
	ds_read_b128 v[180:183], v154 offset:2048
	ds_read_b128 v[184:187], v154 offset:3072
	v_add_u32_e32 v154, s12, v163
	ds_read_b128 v[188:191], v154
	ds_read_b128 v[192:195], v154 offset:1024
	ds_read_b128 v[196:199], v154 offset:2048
	ds_read_b128 v[200:203], v154 offset:3072
	s_mov_b32 m0, s20
	v_lshl_add_u64 v[206:207], v[164:165], 0, s[54:55]
	ds_read_b128 v[210:213], v169 offset:32768
	ds_read_b128 v[214:217], v169 offset:33792
	ds_read_b128 v[218:221], v169 offset:34816
	ds_read_b128 v[222:225], v169 offset:35840
	ds_read_b128 v[226:229], v169 offset:36864
	ds_read_b128 v[230:233], v169 offset:37888
	ds_read_b128 v[234:237], v169 offset:38912
	ds_read_b128 v[250:253], v169 offset:39936
	global_load_lds_dwordx4 v[206:207], off
	v_lshl_add_u64 v[206:207], v[164:165], 0, s[56:57]
	s_mov_b32 m0, s21
	s_nop 0
	global_load_lds_dwordx4 v[206:207], off
	s_waitcnt vmcnt(8)
	s_waitcnt lgkmcnt(0)
	s_barrier
	s_setprio 1
	s_waitcnt lgkmcnt(0)
	v_mfma_f32_16x16x32_bf16 v[126:129], v[172:175], v[210:213], v[126:129]
	v_mfma_f32_16x16x32_bf16 v[122:125], v[180:183], v[210:213], v[122:125]
	v_mfma_f32_16x16x32_bf16 v[110:113], v[172:175], v[218:221], v[110:113]
	v_mfma_f32_16x16x32_bf16 v[106:109], v[180:183], v[218:221], v[106:109]
	v_mfma_f32_16x16x32_bf16 v[94:97], v[172:175], v[226:229], v[94:97]
	v_mfma_f32_16x16x32_bf16 v[90:93], v[180:183], v[226:229], v[90:93]
	v_mfma_f32_16x16x32_bf16 v[78:81], v[172:175], v[234:237], v[78:81]
	v_mfma_f32_16x16x32_bf16 v[74:77], v[180:183], v[234:237], v[74:77]
	v_mfma_f32_16x16x32_bf16 v[126:129], v[176:179], v[214:217], v[126:129]
	v_mfma_f32_16x16x32_bf16 v[122:125], v[184:187], v[214:217], v[122:125]
	v_mfma_f32_16x16x32_bf16 v[110:113], v[176:179], v[222:225], v[110:113]
	v_mfma_f32_16x16x32_bf16 v[106:109], v[184:187], v[222:225], v[106:109]
	v_mfma_f32_16x16x32_bf16 v[94:97], v[176:179], v[230:233], v[94:97]
	v_mfma_f32_16x16x32_bf16 v[90:93], v[184:187], v[230:233], v[90:93]
	v_mfma_f32_16x16x32_bf16 v[78:81], v[176:179], v[250:253], v[78:81]
	v_mfma_f32_16x16x32_bf16 v[74:77], v[184:187], v[250:253], v[74:77]
	s_setprio 0
	s_setprio 1
	v_mfma_f32_16x16x32_bf16 v[118:121], v[188:191], v[210:213], v[118:121]
	v_mfma_f32_16x16x32_bf16 v[114:117], v[196:199], v[210:213], v[114:117]
	v_mfma_f32_16x16x32_bf16 v[102:105], v[188:191], v[218:221], v[102:105]
	v_mfma_f32_16x16x32_bf16 v[98:101], v[196:199], v[218:221], v[98:101]
	v_mfma_f32_16x16x32_bf16 v[86:89], v[188:191], v[226:229], v[86:89]
	v_mfma_f32_16x16x32_bf16 v[82:85], v[196:199], v[226:229], v[82:85]
	v_mfma_f32_16x16x32_bf16 v[70:73], v[188:191], v[234:237], v[70:73]
	v_mfma_f32_16x16x32_bf16 v[66:69], v[196:199], v[234:237], v[66:69]
	v_mfma_f32_16x16x32_bf16 v[118:121], v[192:195], v[214:217], v[118:121]
	v_mfma_f32_16x16x32_bf16 v[114:117], v[200:203], v[214:217], v[114:117]
	v_mfma_f32_16x16x32_bf16 v[102:105], v[192:195], v[222:225], v[102:105]
	v_mfma_f32_16x16x32_bf16 v[98:101], v[200:203], v[222:225], v[98:101]
	v_mfma_f32_16x16x32_bf16 v[86:89], v[192:195], v[230:233], v[86:89]
	v_mfma_f32_16x16x32_bf16 v[82:85], v[200:203], v[230:233], v[82:85]
	v_mfma_f32_16x16x32_bf16 v[70:73], v[192:195], v[250:253], v[70:73]
	v_mfma_f32_16x16x32_bf16 v[66:69], v[200:203], v[250:253], v[66:69]
	s_setprio 0
	s_barrier
	s_add_i32 s10, s10, s16
	v_lshl_add_u64 v[206:207], v[204:205], 0, s[62:63]
	s_mov_b32 m0, s10
	ds_read_b128 v[210:213], v169 offset:49152
	ds_read_b128 v[214:217], v169 offset:50176
	global_load_lds_dwordx4 v[206:207], off
	v_lshl_add_u64 v[206:207], v[204:205], 0, s[64:65]
	s_add_i32 m0, s10, 0x2000
	s_add_i32 s10, s12, s16
	ds_read_b128 v[218:221], v169 offset:51200
	ds_read_b128 v[222:225], v169 offset:52224
	global_load_lds_dwordx4 v[206:207], off
	v_lshl_add_u64 v[206:207], v[204:205], 0, s[66:67]
	s_mov_b32 m0, s10
	v_lshl_add_u64 v[204:205], v[204:205], 0, s[68:69]
	ds_read_b128 v[226:229], v169 offset:53248
	ds_read_b128 v[230:233], v169 offset:54272
	global_load_lds_dwordx4 v[206:207], off
	s_add_i32 m0, s10, 0x2000
	s_nop 0
	ds_read_b128 v[234:237], v169 offset:55296
	ds_read_b128 v[250:253], v169 offset:56320
	global_load_lds_dwordx4 v[204:205], off
	v_lshl_add_u64 v[204:205], v[164:165], 0, s[62:63]
	s_mov_b32 m0, s22
	v_lshl_add_u64 v[164:165], v[164:165], 0, s[64:65]
	global_load_lds_dwordx4 v[204:205], off
	s_mov_b32 m0, s23
	s_nop 0
	global_load_lds_dwordx4 v[164:165], off
	s_waitcnt vmcnt(8)
	s_waitcnt lgkmcnt(0)
	s_barrier
	s_setprio 1
	s_waitcnt lgkmcnt(0)
	v_mfma_f32_16x16x32_bf16 v[62:65], v[172:175], v[210:213], v[62:65]
	v_mfma_f32_16x16x32_bf16 v[58:61], v[180:183], v[210:213], v[58:61]
	v_mfma_f32_16x16x32_bf16 v[46:49], v[172:175], v[218:221], v[46:49]
	v_mfma_f32_16x16x32_bf16 v[42:45], v[180:183], v[218:221], v[42:45]
	v_mfma_f32_16x16x32_bf16 v[30:33], v[172:175], v[226:229], v[30:33]
	v_mfma_f32_16x16x32_bf16 v[26:29], v[180:183], v[226:229], v[26:29]
	v_mfma_f32_16x16x32_bf16 v[14:17], v[172:175], v[234:237], v[14:17]
	v_mfma_f32_16x16x32_bf16 v[10:13], v[180:183], v[234:237], v[10:13]
	v_mfma_f32_16x16x32_bf16 v[62:65], v[176:179], v[214:217], v[62:65]
	v_mfma_f32_16x16x32_bf16 v[58:61], v[184:187], v[214:217], v[58:61]
	v_mfma_f32_16x16x32_bf16 v[46:49], v[176:179], v[222:225], v[46:49]
	v_mfma_f32_16x16x32_bf16 v[42:45], v[184:187], v[222:225], v[42:45]
	v_mfma_f32_16x16x32_bf16 v[30:33], v[176:179], v[230:233], v[30:33]
	v_mfma_f32_16x16x32_bf16 v[26:29], v[184:187], v[230:233], v[26:29]
	v_mfma_f32_16x16x32_bf16 v[14:17], v[176:179], v[250:253], v[14:17]
	v_mfma_f32_16x16x32_bf16 v[10:13], v[184:187], v[250:253], v[10:13]
	s_setprio 0
	s_setprio 1
	v_mfma_f32_16x16x32_bf16 v[54:57], v[188:191], v[210:213], v[54:57]
	v_mfma_f32_16x16x32_bf16 v[50:53], v[196:199], v[210:213], v[50:53]
	v_mfma_f32_16x16x32_bf16 v[38:41], v[188:191], v[218:221], v[38:41]
	v_mfma_f32_16x16x32_bf16 v[34:37], v[196:199], v[218:221], v[34:37]
	v_mfma_f32_16x16x32_bf16 v[22:25], v[188:191], v[226:229], v[22:25]
	v_mfma_f32_16x16x32_bf16 v[18:21], v[196:199], v[226:229], v[18:21]
	v_mfma_f32_16x16x32_bf16 v[2:5], v[188:191], v[234:237], v[2:5]
	v_mfma_f32_16x16x32_bf16 v[6:9], v[196:199], v[234:237], v[6:9]
	v_mfma_f32_16x16x32_bf16 v[54:57], v[192:195], v[214:217], v[54:57]
	v_mfma_f32_16x16x32_bf16 v[50:53], v[200:203], v[214:217], v[50:53]
	v_mfma_f32_16x16x32_bf16 v[38:41], v[192:195], v[222:225], v[38:41]
	v_mfma_f32_16x16x32_bf16 v[34:37], v[200:203], v[222:225], v[34:37]
	v_mfma_f32_16x16x32_bf16 v[22:25], v[192:195], v[230:233], v[22:25]
	v_mfma_f32_16x16x32_bf16 v[18:21], v[200:203], v[230:233], v[18:21]
	v_mfma_f32_16x16x32_bf16 v[2:5], v[192:195], v[250:253], v[2:5]
	v_mfma_f32_16x16x32_bf16 v[6:9], v[200:203], v[250:253], v[6:9]
	s_setprio 0
	s_barrier
	s_add_i32 s9, s9, 2
	v_lshl_add_u64 v[150:151], v[150:151], 0, s[72:73]
	s_cmp_gt_u32 s9, 29
	v_lshl_add_u64 v[148:149], v[148:149], 0, s[72:73]
	s_cbranch_scc1 .LBB0_1167

.LBB0_1234:
	s_cmpk_eq_i32 s9, 0x7c
	s_cselect_b64 vcc, -1, 0
	s_add_i32 s11, 0, 0x10000
	v_lshl_add_u64 v[142:143], v[140:141], 0, s[48:49]
	v_add_u32_e32 v138, s11, v251
	s_add_i32 s13, 0, 0x14000
	v_cndmask_b32_e32 v207, v143, v137, vcc
	v_cndmask_b32_e32 v206, v142, v0, vcc
	ds_read_b128 v[142:145], v138
	ds_read_b128 v[146:149], v138 offset:1024
	ds_read_b128 v[150:153], v138 offset:2048
	ds_read_b128 v[154:157], v138 offset:3072
	v_add_u32_e32 v138, s13, v251
	ds_read_b128 v[158:161], v138
	ds_read_b128 v[162:165], v138 offset:1024
	ds_read_b128 v[166:169], v138 offset:2048
	ds_read_b128 v[170:173], v138 offset:3072
	v_cndmask_b32_e32 v227, v135, v139, vcc
	v_cndmask_b32_e32 v226, v134, v136, vcc
	v_lshl_add_u64 v[228:229], v[140:141], 0, v[212:213]
	s_add_i32 m0, s21, 0xc000
	ds_read_b128 v[174:177], v253
	ds_read_b128 v[178:181], v253 offset:1024
	ds_read_b128 v[182:185], v253 offset:2048
	ds_read_b128 v[186:189], v253 offset:3072
	ds_read_b128 v[190:193], v253 offset:4096
	ds_read_b128 v[194:197], v253 offset:5120
	ds_read_b128 v[218:221], v253 offset:6144
	ds_read_b128 v[222:225], v253 offset:7168
	global_load_lds_dwordx4 v[228:229], off
	v_lshl_add_u64 v[228:229], v[228:229], 0, s[84:85]
	s_add_i32 m0, s21, 0xe000
	s_nop 0
	global_load_lds_dwordx4 v[228:229], off
	s_waitcnt vmcnt(8)
	s_waitcnt lgkmcnt(0)
	s_barrier
	s_setprio 1
	s_waitcnt lgkmcnt(0)
	v_mfma_f32_16x16x32_bf16 v[126:129], v[142:145], v[174:177], v[126:129]
	v_mfma_f32_16x16x32_bf16 v[130:133], v[150:153], v[174:177], v[130:133]
	v_mfma_f32_16x16x32_bf16 v[114:117], v[142:145], v[182:185], v[114:117]
	v_mfma_f32_16x16x32_bf16 v[110:113], v[150:153], v[182:185], v[110:113]
	v_mfma_f32_16x16x32_bf16 v[98:101], v[142:145], v[190:193], v[98:101]
	v_mfma_f32_16x16x32_bf16 v[94:97], v[150:153], v[190:193], v[94:97]
	v_mfma_f32_16x16x32_bf16 v[82:85], v[142:145], v[218:221], v[82:85]
	v_mfma_f32_16x16x32_bf16 v[78:81], v[150:153], v[218:221], v[78:81]
	v_mfma_f32_16x16x32_bf16 v[126:129], v[146:149], v[178:181], v[126:129]
	v_mfma_f32_16x16x32_bf16 v[130:133], v[154:157], v[178:181], v[130:133]
	v_mfma_f32_16x16x32_bf16 v[114:117], v[146:149], v[186:189], v[114:117]
	v_mfma_f32_16x16x32_bf16 v[110:113], v[154:157], v[186:189], v[110:113]
	v_mfma_f32_16x16x32_bf16 v[98:101], v[146:149], v[194:197], v[98:101]
	v_mfma_f32_16x16x32_bf16 v[94:97], v[154:157], v[194:197], v[94:97]
	v_mfma_f32_16x16x32_bf16 v[82:85], v[146:149], v[222:225], v[82:85]
	v_mfma_f32_16x16x32_bf16 v[78:81], v[154:157], v[222:225], v[78:81]
	s_setprio 0
	s_setprio 1
	v_mfma_f32_16x16x32_bf16 v[122:125], v[158:161], v[174:177], v[122:125]
	v_mfma_f32_16x16x32_bf16 v[118:121], v[166:169], v[174:177], v[118:121]
	v_mfma_f32_16x16x32_bf16 v[106:109], v[158:161], v[182:185], v[106:109]
	v_mfma_f32_16x16x32_bf16 v[102:105], v[166:169], v[182:185], v[102:105]
	v_mfma_f32_16x16x32_bf16 v[90:93], v[158:161], v[190:193], v[90:93]
	v_mfma_f32_16x16x32_bf16 v[86:89], v[166:169], v[190:193], v[86:89]
	v_mfma_f32_16x16x32_bf16 v[74:77], v[158:161], v[218:221], v[74:77]
	v_mfma_f32_16x16x32_bf16 v[70:73], v[166:169], v[218:221], v[70:73]
	v_mfma_f32_16x16x32_bf16 v[122:125], v[162:165], v[178:181], v[122:125]
	v_mfma_f32_16x16x32_bf16 v[118:121], v[170:173], v[178:181], v[118:121]
	v_mfma_f32_16x16x32_bf16 v[106:109], v[162:165], v[186:189], v[106:109]
	v_mfma_f32_16x16x32_bf16 v[102:105], v[170:173], v[186:189], v[102:105]
	v_mfma_f32_16x16x32_bf16 v[90:93], v[162:165], v[194:197], v[90:93]
	v_mfma_f32_16x16x32_bf16 v[86:89], v[170:173], v[194:197], v[86:89]
	v_mfma_f32_16x16x32_bf16 v[74:77], v[162:165], v[222:225], v[74:77]
	v_mfma_f32_16x16x32_bf16 v[70:73], v[170:173], v[222:225], v[70:73]
	s_setprio 0
	s_barrier
	s_add_i32 s11, s11, s20
	v_lshl_add_u64 v[226:227], v[226:227], 0, v[210:211]
	s_mov_b32 m0, s11
	ds_read_b128 v[174:177], v253 offset:16384
	ds_read_b128 v[178:181], v253 offset:17408
	global_load_lds_dwordx4 v[226:227], off
	v_lshl_add_u64 v[228:229], v[226:227], 0, s[84:85]
	s_add_i32 m0, s11, 0x2000
	s_add_i32 s11, s13, s20
	ds_read_b128 v[182:185], v253 offset:18432
	ds_read_b128 v[186:189], v253 offset:19456
	global_load_lds_dwordx4 v[228:229], off
	v_lshl_add_u64 v[228:229], v[226:227], 0, s[50:51]
	s_mov_b32 m0, s11
	v_lshl_add_u64 v[206:207], v[206:207], 0, v[204:205]
	ds_read_b128 v[190:193], v253 offset:20480
	ds_read_b128 v[194:197], v253 offset:21504
	global_load_lds_dwordx4 v[228:229], off
	v_lshl_add_u64 v[228:229], v[226:227], 0, s[94:95]
	s_add_i32 m0, s11, 0x2000
	s_nop 0
	ds_read_b128 v[218:221], v253 offset:22528
	ds_read_b128 v[222:225], v253 offset:23552
	global_load_lds_dwordx4 v[228:229], off
	s_mov_b32 m0, s21
	v_lshl_add_u64 v[228:229], v[206:207], 0, s[84:85]
	global_load_lds_dwordx4 v[206:207], off
	s_mov_b32 m0, s22
	s_nop 0
	global_load_lds_dwordx4 v[228:229], off
	s_waitcnt vmcnt(8)
	s_waitcnt lgkmcnt(0)
	s_barrier
	s_setprio 1
	s_waitcnt lgkmcnt(0)
	v_mfma_f32_16x16x32_bf16 v[66:69], v[142:145], v[174:177], v[66:69]
	v_mfma_f32_16x16x32_bf16 v[62:65], v[150:153], v[174:177], v[62:65]
	v_mfma_f32_16x16x32_bf16 v[50:53], v[142:145], v[182:185], v[50:53]
	v_mfma_f32_16x16x32_bf16 v[46:49], v[150:153], v[182:185], v[46:49]
	v_mfma_f32_16x16x32_bf16 v[34:37], v[142:145], v[190:193], v[34:37]
	v_mfma_f32_16x16x32_bf16 v[30:33], v[150:153], v[190:193], v[30:33]
	v_mfma_f32_16x16x32_bf16 v[18:21], v[142:145], v[218:221], v[18:21]
	v_mfma_f32_16x16x32_bf16 v[14:17], v[150:153], v[218:221], v[14:17]
	v_mfma_f32_16x16x32_bf16 v[66:69], v[146:149], v[178:181], v[66:69]
	v_mfma_f32_16x16x32_bf16 v[62:65], v[154:157], v[178:181], v[62:65]
	v_mfma_f32_16x16x32_bf16 v[50:53], v[146:149], v[186:189], v[50:53]
	v_mfma_f32_16x16x32_bf16 v[46:49], v[154:157], v[186:189], v[46:49]
	v_mfma_f32_16x16x32_bf16 v[34:37], v[146:149], v[194:197], v[34:37]
	v_mfma_f32_16x16x32_bf16 v[30:33], v[154:157], v[194:197], v[30:33]
	v_mfma_f32_16x16x32_bf16 v[18:21], v[146:149], v[222:225], v[18:21]
	v_mfma_f32_16x16x32_bf16 v[14:17], v[154:157], v[222:225], v[14:17]
	s_setprio 0
	s_setprio 1
	v_mfma_f32_16x16x32_bf16 v[58:61], v[158:161], v[174:177], v[58:61]
	v_mfma_f32_16x16x32_bf16 v[54:57], v[166:169], v[174:177], v[54:57]
	v_mfma_f32_16x16x32_bf16 v[42:45], v[158:161], v[182:185], v[42:45]
	v_mfma_f32_16x16x32_bf16 v[38:41], v[166:169], v[182:185], v[38:41]
	v_mfma_f32_16x16x32_bf16 v[26:29], v[158:161], v[190:193], v[26:29]
	v_mfma_f32_16x16x32_bf16 v[22:25], v[166:169], v[190:193], v[22:25]
	v_mfma_f32_16x16x32_bf16 v[10:13], v[158:161], v[218:221], v[10:13]
	v_mfma_f32_16x16x32_bf16 v[6:9], v[166:169], v[218:221], v[6:9]
	v_mfma_f32_16x16x32_bf16 v[58:61], v[162:165], v[178:181], v[58:61]
	v_mfma_f32_16x16x32_bf16 v[54:57], v[170:173], v[178:181], v[54:57]
	v_mfma_f32_16x16x32_bf16 v[42:45], v[162:165], v[186:189], v[42:45]
	v_mfma_f32_16x16x32_bf16 v[38:41], v[170:173], v[186:189], v[38:41]
	v_mfma_f32_16x16x32_bf16 v[26:29], v[162:165], v[194:197], v[26:29]
	v_mfma_f32_16x16x32_bf16 v[22:25], v[170:173], v[194:197], v[22:25]
	v_mfma_f32_16x16x32_bf16 v[10:13], v[162:165], v[222:225], v[10:13]
	v_mfma_f32_16x16x32_bf16 v[6:9], v[170:173], v[222:225], v[6:9]
	s_setprio 0
	s_barrier
	s_add_i32 s11, 0, 0x18000
	v_add_u32_e32 v138, s11, v251
	s_add_i32 s13, 0, 0x1c000
	ds_read_b128 v[142:145], v138
	ds_read_b128 v[146:149], v138 offset:1024
	ds_read_b128 v[150:153], v138 offset:2048
	ds_read_b128 v[154:157], v138 offset:3072
	v_add_u32_e32 v138, s13, v251
	ds_read_b128 v[158:161], v138
	ds_read_b128 v[162:165], v138 offset:1024
	ds_read_b128 v[166:169], v138 offset:2048
	ds_read_b128 v[170:173], v138 offset:3072
	s_mov_b32 m0, s23
	v_lshl_add_u64 v[228:229], v[206:207], 0, s[50:51]
	ds_read_b128 v[174:177], v253 offset:32768
	ds_read_b128 v[178:181], v253 offset:33792
	ds_read_b128 v[182:185], v253 offset:34816
	ds_read_b128 v[186:189], v253 offset:35840
	ds_read_b128 v[190:193], v253 offset:36864
	ds_read_b128 v[194:197], v253 offset:37888
	ds_read_b128 v[218:221], v253 offset:38912
	ds_read_b128 v[222:225], v253 offset:39936
	global_load_lds_dwordx4 v[228:229], off
	v_lshl_add_u64 v[228:229], v[206:207], 0, s[94:95]
	s_mov_b32 m0, s24
	s_nop 0
	global_load_lds_dwordx4 v[228:229], off
	s_waitcnt vmcnt(8)
	s_waitcnt lgkmcnt(0)
	s_barrier
	s_setprio 1
	s_waitcnt lgkmcnt(0)
	v_mfma_f32_16x16x32_bf16 v[126:129], v[142:145], v[174:177], v[126:129]
	v_mfma_f32_16x16x32_bf16 v[130:133], v[150:153], v[174:177], v[130:133]
	v_mfma_f32_16x16x32_bf16 v[114:117], v[142:145], v[182:185], v[114:117]
	v_mfma_f32_16x16x32_bf16 v[110:113], v[150:153], v[182:185], v[110:113]
	v_mfma_f32_16x16x32_bf16 v[98:101], v[142:145], v[190:193], v[98:101]
	v_mfma_f32_16x16x32_bf16 v[94:97], v[150:153], v[190:193], v[94:97]
	v_mfma_f32_16x16x32_bf16 v[82:85], v[142:145], v[218:221], v[82:85]
	v_mfma_f32_16x16x32_bf16 v[78:81], v[150:153], v[218:221], v[78:81]
	v_mfma_f32_16x16x32_bf16 v[126:129], v[146:149], v[178:181], v[126:129]
	v_mfma_f32_16x16x32_bf16 v[130:133], v[154:157], v[178:181], v[130:133]
	v_mfma_f32_16x16x32_bf16 v[114:117], v[146:149], v[186:189], v[114:117]
	v_mfma_f32_16x16x32_bf16 v[110:113], v[154:157], v[186:189], v[110:113]
	v_mfma_f32_16x16x32_bf16 v[98:101], v[146:149], v[194:197], v[98:101]
	v_mfma_f32_16x16x32_bf16 v[94:97], v[154:157], v[194:197], v[94:97]
	v_mfma_f32_16x16x32_bf16 v[82:85], v[146:149], v[222:225], v[82:85]
	v_mfma_f32_16x16x32_bf16 v[78:81], v[154:157], v[222:225], v[78:81]
	s_setprio 0
	s_setprio 1
	v_mfma_f32_16x16x32_bf16 v[122:125], v[158:161], v[174:177], v[122:125]
	v_mfma_f32_16x16x32_bf16 v[118:121], v[166:169], v[174:177], v[118:121]
	v_mfma_f32_16x16x32_bf16 v[106:109], v[158:161], v[182:185], v[106:109]
	v_mfma_f32_16x16x32_bf16 v[102:105], v[166:169], v[182:185], v[102:105]
	v_mfma_f32_16x16x32_bf16 v[90:93], v[158:161], v[190:193], v[90:93]
	v_mfma_f32_16x16x32_bf16 v[86:89], v[166:169], v[190:193], v[86:89]
	v_mfma_f32_16x16x32_bf16 v[74:77], v[158:161], v[218:221], v[74:77]
	v_mfma_f32_16x16x32_bf16 v[70:73], v[166:169], v[218:221], v[70:73]
	v_mfma_f32_16x16x32_bf16 v[122:125], v[162:165], v[178:181], v[122:125]
	v_mfma_f32_16x16x32_bf16 v[118:121], v[170:173], v[178:181], v[118:121]
	v_mfma_f32_16x16x32_bf16 v[106:109], v[162:165], v[186:189], v[106:109]
	v_mfma_f32_16x16x32_bf16 v[102:105], v[170:173], v[186:189], v[102:105]
	v_mfma_f32_16x16x32_bf16 v[90:93], v[162:165], v[194:197], v[90:93]
	v_mfma_f32_16x16x32_bf16 v[86:89], v[170:173], v[194:197], v[86:89]
	v_mfma_f32_16x16x32_bf16 v[74:77], v[162:165], v[222:225], v[74:77]
	v_mfma_f32_16x16x32_bf16 v[70:73], v[170:173], v[222:225], v[70:73]
	s_setprio 0
	s_barrier
	s_add_i32 s11, s11, s20
	v_lshl_add_u64 v[228:229], v[226:227], 0, s[62:63]
	s_mov_b32 m0, s11
	ds_read_b128 v[174:177], v253 offset:49152
	ds_read_b128 v[178:181], v253 offset:50176
	global_load_lds_dwordx4 v[228:229], off
	v_lshl_add_u64 v[228:229], v[226:227], 0, s[70:71]
	s_add_i32 m0, s11, 0x2000
	s_add_i32 s11, s13, s20
	ds_read_b128 v[182:185], v253 offset:51200
	ds_read_b128 v[186:189], v253 offset:52224
	global_load_lds_dwordx4 v[228:229], off
	v_lshl_add_u64 v[228:229], v[226:227], 0, s[96:97]
	s_mov_b32 m0, s11
	v_lshl_add_u64 v[226:227], v[226:227], 0, s[88:89]
	ds_read_b128 v[190:193], v253 offset:53248
	ds_read_b128 v[194:197], v253 offset:54272
	global_load_lds_dwordx4 v[228:229], off
	s_add_i32 m0, s11, 0x2000
	s_nop 0
	ds_read_b128 v[218:221], v253 offset:55296
	ds_read_b128 v[222:225], v253 offset:56320
	global_load_lds_dwordx4 v[226:227], off
	v_lshl_add_u64 v[226:227], v[206:207], 0, s[62:63]
	s_mov_b32 m0, s25
	v_lshl_add_u64 v[206:207], v[206:207], 0, s[70:71]
	global_load_lds_dwordx4 v[226:227], off
	s_mov_b32 m0, s26
	s_nop 0
	global_load_lds_dwordx4 v[206:207], off
	s_waitcnt vmcnt(8)
	s_waitcnt lgkmcnt(0)
	s_barrier
	s_setprio 1
	s_waitcnt lgkmcnt(0)
	v_mfma_f32_16x16x32_bf16 v[66:69], v[142:145], v[174:177], v[66:69]
	v_mfma_f32_16x16x32_bf16 v[62:65], v[150:153], v[174:177], v[62:65]
	v_mfma_f32_16x16x32_bf16 v[50:53], v[142:145], v[182:185], v[50:53]
	v_mfma_f32_16x16x32_bf16 v[46:49], v[150:153], v[182:185], v[46:49]
	v_mfma_f32_16x16x32_bf16 v[34:37], v[142:145], v[190:193], v[34:37]
	v_mfma_f32_16x16x32_bf16 v[30:33], v[150:153], v[190:193], v[30:33]
	v_mfma_f32_16x16x32_bf16 v[18:21], v[142:145], v[218:221], v[18:21]
	v_mfma_f32_16x16x32_bf16 v[14:17], v[150:153], v[218:221], v[14:17]
	v_mfma_f32_16x16x32_bf16 v[66:69], v[146:149], v[178:181], v[66:69]
	v_mfma_f32_16x16x32_bf16 v[62:65], v[154:157], v[178:181], v[62:65]
	v_mfma_f32_16x16x32_bf16 v[50:53], v[146:149], v[186:189], v[50:53]
	v_mfma_f32_16x16x32_bf16 v[46:49], v[154:157], v[186:189], v[46:49]
	v_mfma_f32_16x16x32_bf16 v[34:37], v[146:149], v[194:197], v[34:37]
	v_mfma_f32_16x16x32_bf16 v[30:33], v[154:157], v[194:197], v[30:33]
	v_mfma_f32_16x16x32_bf16 v[18:21], v[146:149], v[222:225], v[18:21]
	v_mfma_f32_16x16x32_bf16 v[14:17], v[154:157], v[222:225], v[14:17]
	s_setprio 0
	s_setprio 1
	v_mfma_f32_16x16x32_bf16 v[58:61], v[158:161], v[174:177], v[58:61]
	v_mfma_f32_16x16x32_bf16 v[54:57], v[166:169], v[174:177], v[54:57]
	v_mfma_f32_16x16x32_bf16 v[42:45], v[158:161], v[182:185], v[42:45]
	v_mfma_f32_16x16x32_bf16 v[38:41], v[166:169], v[182:185], v[38:41]
	v_mfma_f32_16x16x32_bf16 v[26:29], v[158:161], v[190:193], v[26:29]
	v_mfma_f32_16x16x32_bf16 v[22:25], v[166:169], v[190:193], v[22:25]
	v_mfma_f32_16x16x32_bf16 v[10:13], v[158:161], v[218:221], v[10:13]
	v_mfma_f32_16x16x32_bf16 v[6:9], v[166:169], v[218:221], v[6:9]
	v_mfma_f32_16x16x32_bf16 v[58:61], v[162:165], v[178:181], v[58:61]
	v_mfma_f32_16x16x32_bf16 v[54:57], v[170:173], v[178:181], v[54:57]
	v_mfma_f32_16x16x32_bf16 v[42:45], v[162:165], v[186:189], v[42:45]
	v_mfma_f32_16x16x32_bf16 v[38:41], v[170:173], v[186:189], v[38:41]
	v_mfma_f32_16x16x32_bf16 v[26:29], v[162:165], v[194:197], v[26:29]
	v_mfma_f32_16x16x32_bf16 v[22:25], v[170:173], v[194:197], v[22:25]
	v_mfma_f32_16x16x32_bf16 v[10:13], v[162:165], v[222:225], v[10:13]
	v_mfma_f32_16x16x32_bf16 v[6:9], v[170:173], v[222:225], v[6:9]
	s_setprio 0
	s_barrier
	s_add_i32 s9, s9, 2
	v_lshl_add_u64 v[140:141], v[140:141], 0, s[72:73]
	s_cmpk_gt_u32 s9, 0x7d
	v_lshl_add_u64 v[134:135], v[134:135], 0, s[72:73]
	s_cbranch_scc0 .LBB0_1234
	v_mov_b64_e32 v[242:243], 0x500
	s_and_b64 vcc, exec, s[2:3]
	s_cbranch_vccz .LBB0_1237
	s_barrier

.LBB0_1268:
	s_cmpk_eq_i32 s7, 0x7c
	s_cselect_b64 vcc, -1, 0
	s_add_i32 s9, 0, 0x10000
	v_lshl_add_u64 v[140:141], v[138:139], 0, s[48:49]
	v_add_u32_e32 v136, s9, v231
	s_add_i32 s12, 0, 0x14000
	v_cndmask_b32_e32 v207, v141, v135, vcc
	v_cndmask_b32_e32 v206, v140, v0, vcc
	ds_read_b128 v[140:143], v136
	ds_read_b128 v[144:147], v136 offset:1024
	ds_read_b128 v[148:151], v136 offset:2048
	ds_read_b128 v[152:155], v136 offset:3072
	v_add_u32_e32 v136, s12, v231
	ds_read_b128 v[156:159], v136
	ds_read_b128 v[160:163], v136 offset:1024
	ds_read_b128 v[164:167], v136 offset:2048
	ds_read_b128 v[168:171], v136 offset:3072
	v_cndmask_b32_e32 v209, v133, v137, vcc
	v_cndmask_b32_e32 v208, v132, v134, vcc
	v_lshl_add_u64 v[224:225], v[138:139], 0, v[196:197]
	s_add_i32 m0, s16, 0xc000
	ds_read_b128 v[172:175], v233
	ds_read_b128 v[176:179], v233 offset:1024
	ds_read_b128 v[180:183], v233 offset:2048
	ds_read_b128 v[184:187], v233 offset:3072
	ds_read_b128 v[188:191], v233 offset:4096
	ds_read_b128 v[212:215], v233 offset:5120
	ds_read_b128 v[216:219], v233 offset:6144
	ds_read_b128 v[220:223], v233 offset:7168
	global_load_lds_dwordx4 v[224:225], off
	v_lshl_add_u64 v[224:225], v[224:225], 0, s[84:85]
	s_add_i32 m0, s16, 0xe000
	s_nop 0
	global_load_lds_dwordx4 v[224:225], off
	s_waitcnt vmcnt(8)
	s_waitcnt lgkmcnt(0)
	s_barrier
	s_setprio 1
	s_waitcnt lgkmcnt(0)
	v_mfma_f32_16x16x32_bf16 v[124:127], v[140:143], v[172:175], v[124:127]
	v_mfma_f32_16x16x32_bf16 v[128:131], v[148:151], v[172:175], v[128:131]
	v_mfma_f32_16x16x32_bf16 v[112:115], v[140:143], v[180:183], v[112:115]
	v_mfma_f32_16x16x32_bf16 v[108:111], v[148:151], v[180:183], v[108:111]
	v_mfma_f32_16x16x32_bf16 v[96:99], v[140:143], v[188:191], v[96:99]
	v_mfma_f32_16x16x32_bf16 v[92:95], v[148:151], v[188:191], v[92:95]
	v_mfma_f32_16x16x32_bf16 v[80:83], v[140:143], v[216:219], v[80:83]
	v_mfma_f32_16x16x32_bf16 v[76:79], v[148:151], v[216:219], v[76:79]
	v_mfma_f32_16x16x32_bf16 v[124:127], v[144:147], v[176:179], v[124:127]
	v_mfma_f32_16x16x32_bf16 v[128:131], v[152:155], v[176:179], v[128:131]
	v_mfma_f32_16x16x32_bf16 v[112:115], v[144:147], v[184:187], v[112:115]
	v_mfma_f32_16x16x32_bf16 v[108:111], v[152:155], v[184:187], v[108:111]
	v_mfma_f32_16x16x32_bf16 v[96:99], v[144:147], v[212:215], v[96:99]
	v_mfma_f32_16x16x32_bf16 v[92:95], v[152:155], v[212:215], v[92:95]
	v_mfma_f32_16x16x32_bf16 v[80:83], v[144:147], v[220:223], v[80:83]
	v_mfma_f32_16x16x32_bf16 v[76:79], v[152:155], v[220:223], v[76:79]
	s_setprio 0
	s_setprio 1
	v_mfma_f32_16x16x32_bf16 v[120:123], v[156:159], v[172:175], v[120:123]
	v_mfma_f32_16x16x32_bf16 v[116:119], v[164:167], v[172:175], v[116:119]
	v_mfma_f32_16x16x32_bf16 v[104:107], v[156:159], v[180:183], v[104:107]
	v_mfma_f32_16x16x32_bf16 v[100:103], v[164:167], v[180:183], v[100:103]
	v_mfma_f32_16x16x32_bf16 v[88:91], v[156:159], v[188:191], v[88:91]
	v_mfma_f32_16x16x32_bf16 v[84:87], v[164:167], v[188:191], v[84:87]
	v_mfma_f32_16x16x32_bf16 v[72:75], v[156:159], v[216:219], v[72:75]
	v_mfma_f32_16x16x32_bf16 v[68:71], v[164:167], v[216:219], v[68:71]
	v_mfma_f32_16x16x32_bf16 v[120:123], v[160:163], v[176:179], v[120:123]
	v_mfma_f32_16x16x32_bf16 v[116:119], v[168:171], v[176:179], v[116:119]
	v_mfma_f32_16x16x32_bf16 v[104:107], v[160:163], v[184:187], v[104:107]
	v_mfma_f32_16x16x32_bf16 v[100:103], v[168:171], v[184:187], v[100:103]
	v_mfma_f32_16x16x32_bf16 v[88:91], v[160:163], v[212:215], v[88:91]
	v_mfma_f32_16x16x32_bf16 v[84:87], v[168:171], v[212:215], v[84:87]
	v_mfma_f32_16x16x32_bf16 v[72:75], v[160:163], v[220:223], v[72:75]
	v_mfma_f32_16x16x32_bf16 v[68:71], v[168:171], v[220:223], v[68:71]
	s_setprio 0
	s_barrier
	s_add_i32 s9, s9, s14
	v_lshl_add_u64 v[208:209], v[208:209], 0, v[192:193]
	s_mov_b32 m0, s9
	ds_read_b128 v[172:175], v233 offset:16384
	ds_read_b128 v[176:179], v233 offset:17408
	global_load_lds_dwordx4 v[208:209], off
	v_lshl_add_u64 v[224:225], v[208:209], 0, s[84:85]
	s_add_i32 m0, s9, 0x2000
	s_add_i32 s9, s12, s14
	ds_read_b128 v[180:183], v233 offset:18432
	ds_read_b128 v[184:187], v233 offset:19456
	global_load_lds_dwordx4 v[224:225], off
	v_lshl_add_u64 v[224:225], v[208:209], 0, s[50:51]
	s_mov_b32 m0, s9
	v_lshl_add_u64 v[206:207], v[206:207], 0, v[194:195]
	ds_read_b128 v[188:191], v233 offset:20480
	ds_read_b128 v[212:215], v233 offset:21504
	global_load_lds_dwordx4 v[224:225], off
	v_lshl_add_u64 v[224:225], v[208:209], 0, s[94:95]
	s_add_i32 m0, s9, 0x2000
	s_nop 0
	ds_read_b128 v[216:219], v233 offset:22528
	ds_read_b128 v[220:223], v233 offset:23552
	global_load_lds_dwordx4 v[224:225], off
	s_mov_b32 m0, s16
	v_lshl_add_u64 v[224:225], v[206:207], 0, s[84:85]
	global_load_lds_dwordx4 v[206:207], off
	s_mov_b32 m0, s17
	s_nop 0
	global_load_lds_dwordx4 v[224:225], off
	s_waitcnt vmcnt(8)
	s_waitcnt lgkmcnt(0)
	s_barrier
	s_setprio 1
	s_waitcnt lgkmcnt(0)
	v_mfma_f32_16x16x32_bf16 v[64:67], v[140:143], v[172:175], v[64:67]
	v_mfma_f32_16x16x32_bf16 v[60:63], v[148:151], v[172:175], v[60:63]
	v_mfma_f32_16x16x32_bf16 v[48:51], v[140:143], v[180:183], v[48:51]
	v_mfma_f32_16x16x32_bf16 v[44:47], v[148:151], v[180:183], v[44:47]
	v_mfma_f32_16x16x32_bf16 v[32:35], v[140:143], v[188:191], v[32:35]
	v_mfma_f32_16x16x32_bf16 v[28:31], v[148:151], v[188:191], v[28:31]
	v_mfma_f32_16x16x32_bf16 v[16:19], v[140:143], v[216:219], v[16:19]
	v_mfma_f32_16x16x32_bf16 v[12:15], v[148:151], v[216:219], v[12:15]
	v_mfma_f32_16x16x32_bf16 v[64:67], v[144:147], v[176:179], v[64:67]
	v_mfma_f32_16x16x32_bf16 v[60:63], v[152:155], v[176:179], v[60:63]
	v_mfma_f32_16x16x32_bf16 v[48:51], v[144:147], v[184:187], v[48:51]
	v_mfma_f32_16x16x32_bf16 v[44:47], v[152:155], v[184:187], v[44:47]
	v_mfma_f32_16x16x32_bf16 v[32:35], v[144:147], v[212:215], v[32:35]
	v_mfma_f32_16x16x32_bf16 v[28:31], v[152:155], v[212:215], v[28:31]
	v_mfma_f32_16x16x32_bf16 v[16:19], v[144:147], v[220:223], v[16:19]
	v_mfma_f32_16x16x32_bf16 v[12:15], v[152:155], v[220:223], v[12:15]
	s_setprio 0
	s_setprio 1
	v_mfma_f32_16x16x32_bf16 v[56:59], v[156:159], v[172:175], v[56:59]
	v_mfma_f32_16x16x32_bf16 v[52:55], v[164:167], v[172:175], v[52:55]
	v_mfma_f32_16x16x32_bf16 v[40:43], v[156:159], v[180:183], v[40:43]
	v_mfma_f32_16x16x32_bf16 v[36:39], v[164:167], v[180:183], v[36:39]
	v_mfma_f32_16x16x32_bf16 v[24:27], v[156:159], v[188:191], v[24:27]
	v_mfma_f32_16x16x32_bf16 v[20:23], v[164:167], v[188:191], v[20:23]
	v_mfma_f32_16x16x32_bf16 v[8:11], v[156:159], v[216:219], v[8:11]
	v_mfma_f32_16x16x32_bf16 v[4:7], v[164:167], v[216:219], v[4:7]
	v_mfma_f32_16x16x32_bf16 v[56:59], v[160:163], v[176:179], v[56:59]
	v_mfma_f32_16x16x32_bf16 v[52:55], v[168:171], v[176:179], v[52:55]
	v_mfma_f32_16x16x32_bf16 v[40:43], v[160:163], v[184:187], v[40:43]
	v_mfma_f32_16x16x32_bf16 v[36:39], v[168:171], v[184:187], v[36:39]
	v_mfma_f32_16x16x32_bf16 v[24:27], v[160:163], v[212:215], v[24:27]
	v_mfma_f32_16x16x32_bf16 v[20:23], v[168:171], v[212:215], v[20:23]
	v_mfma_f32_16x16x32_bf16 v[8:11], v[160:163], v[220:223], v[8:11]
	v_mfma_f32_16x16x32_bf16 v[4:7], v[168:171], v[220:223], v[4:7]
	s_setprio 0
	s_barrier
	s_add_i32 s9, 0, 0x18000
	v_add_u32_e32 v136, s9, v231
	s_add_i32 s12, 0, 0x1c000
	ds_read_b128 v[140:143], v136
	ds_read_b128 v[144:147], v136 offset:1024
	ds_read_b128 v[148:151], v136 offset:2048
	ds_read_b128 v[152:155], v136 offset:3072
	v_add_u32_e32 v136, s12, v231
	ds_read_b128 v[156:159], v136
	ds_read_b128 v[160:163], v136 offset:1024
	ds_read_b128 v[164:167], v136 offset:2048
	ds_read_b128 v[168:171], v136 offset:3072
	s_mov_b32 m0, s20
	v_lshl_add_u64 v[224:225], v[206:207], 0, s[50:51]
	ds_read_b128 v[172:175], v233 offset:32768
	ds_read_b128 v[176:179], v233 offset:33792
	ds_read_b128 v[180:183], v233 offset:34816
	ds_read_b128 v[184:187], v233 offset:35840
	ds_read_b128 v[188:191], v233 offset:36864
	ds_read_b128 v[212:215], v233 offset:37888
	ds_read_b128 v[216:219], v233 offset:38912
	ds_read_b128 v[220:223], v233 offset:39936
	global_load_lds_dwordx4 v[224:225], off
	v_lshl_add_u64 v[224:225], v[206:207], 0, s[94:95]
	s_mov_b32 m0, s21
	s_nop 0
	global_load_lds_dwordx4 v[224:225], off
	s_waitcnt vmcnt(8)
	s_waitcnt lgkmcnt(0)
	s_barrier
	s_setprio 1
	s_waitcnt lgkmcnt(0)
	v_mfma_f32_16x16x32_bf16 v[124:127], v[140:143], v[172:175], v[124:127]
	v_mfma_f32_16x16x32_bf16 v[128:131], v[148:151], v[172:175], v[128:131]
	v_mfma_f32_16x16x32_bf16 v[112:115], v[140:143], v[180:183], v[112:115]
	v_mfma_f32_16x16x32_bf16 v[108:111], v[148:151], v[180:183], v[108:111]
	v_mfma_f32_16x16x32_bf16 v[96:99], v[140:143], v[188:191], v[96:99]
	v_mfma_f32_16x16x32_bf16 v[92:95], v[148:151], v[188:191], v[92:95]
	v_mfma_f32_16x16x32_bf16 v[80:83], v[140:143], v[216:219], v[80:83]
	v_mfma_f32_16x16x32_bf16 v[76:79], v[148:151], v[216:219], v[76:79]
	v_mfma_f32_16x16x32_bf16 v[124:127], v[144:147], v[176:179], v[124:127]
	v_mfma_f32_16x16x32_bf16 v[128:131], v[152:155], v[176:179], v[128:131]
	v_mfma_f32_16x16x32_bf16 v[112:115], v[144:147], v[184:187], v[112:115]
	v_mfma_f32_16x16x32_bf16 v[108:111], v[152:155], v[184:187], v[108:111]
	v_mfma_f32_16x16x32_bf16 v[96:99], v[144:147], v[212:215], v[96:99]
	v_mfma_f32_16x16x32_bf16 v[92:95], v[152:155], v[212:215], v[92:95]
	v_mfma_f32_16x16x32_bf16 v[80:83], v[144:147], v[220:223], v[80:83]
	v_mfma_f32_16x16x32_bf16 v[76:79], v[152:155], v[220:223], v[76:79]
	s_setprio 0
	s_setprio 1
	v_mfma_f32_16x16x32_bf16 v[120:123], v[156:159], v[172:175], v[120:123]
	v_mfma_f32_16x16x32_bf16 v[116:119], v[164:167], v[172:175], v[116:119]
	v_mfma_f32_16x16x32_bf16 v[104:107], v[156:159], v[180:183], v[104:107]
	v_mfma_f32_16x16x32_bf16 v[100:103], v[164:167], v[180:183], v[100:103]
	v_mfma_f32_16x16x32_bf16 v[88:91], v[156:159], v[188:191], v[88:91]
	v_mfma_f32_16x16x32_bf16 v[84:87], v[164:167], v[188:191], v[84:87]
	v_mfma_f32_16x16x32_bf16 v[72:75], v[156:159], v[216:219], v[72:75]
	v_mfma_f32_16x16x32_bf16 v[68:71], v[164:167], v[216:219], v[68:71]
	v_mfma_f32_16x16x32_bf16 v[120:123], v[160:163], v[176:179], v[120:123]
	v_mfma_f32_16x16x32_bf16 v[116:119], v[168:171], v[176:179], v[116:119]
	v_mfma_f32_16x16x32_bf16 v[104:107], v[160:163], v[184:187], v[104:107]
	v_mfma_f32_16x16x32_bf16 v[100:103], v[168:171], v[184:187], v[100:103]
	v_mfma_f32_16x16x32_bf16 v[88:91], v[160:163], v[212:215], v[88:91]
	v_mfma_f32_16x16x32_bf16 v[84:87], v[168:171], v[212:215], v[84:87]
	v_mfma_f32_16x16x32_bf16 v[72:75], v[160:163], v[220:223], v[72:75]
	v_mfma_f32_16x16x32_bf16 v[68:71], v[168:171], v[220:223], v[68:71]
	s_setprio 0
	s_barrier
	s_add_i32 s9, s9, s14
	v_lshl_add_u64 v[224:225], v[208:209], 0, s[62:63]
	s_mov_b32 m0, s9
	ds_read_b128 v[172:175], v233 offset:49152
	ds_read_b128 v[176:179], v233 offset:50176
	global_load_lds_dwordx4 v[224:225], off
	v_lshl_add_u64 v[224:225], v[208:209], 0, s[70:71]
	s_add_i32 m0, s9, 0x2000
	s_add_i32 s9, s12, s14
	ds_read_b128 v[180:183], v233 offset:51200
	ds_read_b128 v[184:187], v233 offset:52224
	global_load_lds_dwordx4 v[224:225], off
	v_lshl_add_u64 v[224:225], v[208:209], 0, s[96:97]
	s_mov_b32 m0, s9
	v_lshl_add_u64 v[208:209], v[208:209], 0, s[88:89]
	ds_read_b128 v[188:191], v233 offset:53248
	ds_read_b128 v[212:215], v233 offset:54272
	global_load_lds_dwordx4 v[224:225], off
	s_add_i32 m0, s9, 0x2000
	s_nop 0
	ds_read_b128 v[216:219], v233 offset:55296
	ds_read_b128 v[220:223], v233 offset:56320
	global_load_lds_dwordx4 v[208:209], off
	v_lshl_add_u64 v[208:209], v[206:207], 0, s[62:63]
	s_mov_b32 m0, s22
	v_lshl_add_u64 v[206:207], v[206:207], 0, s[70:71]
	global_load_lds_dwordx4 v[208:209], off
	s_mov_b32 m0, s23
	s_nop 0
	global_load_lds_dwordx4 v[206:207], off
	s_waitcnt vmcnt(8)
	s_waitcnt lgkmcnt(0)
	s_barrier
	s_setprio 1
	s_waitcnt lgkmcnt(0)
	v_mfma_f32_16x16x32_bf16 v[64:67], v[140:143], v[172:175], v[64:67]
	v_mfma_f32_16x16x32_bf16 v[60:63], v[148:151], v[172:175], v[60:63]
	v_mfma_f32_16x16x32_bf16 v[48:51], v[140:143], v[180:183], v[48:51]
	v_mfma_f32_16x16x32_bf16 v[44:47], v[148:151], v[180:183], v[44:47]
	v_mfma_f32_16x16x32_bf16 v[32:35], v[140:143], v[188:191], v[32:35]
	v_mfma_f32_16x16x32_bf16 v[28:31], v[148:151], v[188:191], v[28:31]
	v_mfma_f32_16x16x32_bf16 v[16:19], v[140:143], v[216:219], v[16:19]
	v_mfma_f32_16x16x32_bf16 v[12:15], v[148:151], v[216:219], v[12:15]
	v_mfma_f32_16x16x32_bf16 v[64:67], v[144:147], v[176:179], v[64:67]
	v_mfma_f32_16x16x32_bf16 v[60:63], v[152:155], v[176:179], v[60:63]
	v_mfma_f32_16x16x32_bf16 v[48:51], v[144:147], v[184:187], v[48:51]
	v_mfma_f32_16x16x32_bf16 v[44:47], v[152:155], v[184:187], v[44:47]
	v_mfma_f32_16x16x32_bf16 v[32:35], v[144:147], v[212:215], v[32:35]
	v_mfma_f32_16x16x32_bf16 v[28:31], v[152:155], v[212:215], v[28:31]
	v_mfma_f32_16x16x32_bf16 v[16:19], v[144:147], v[220:223], v[16:19]
	v_mfma_f32_16x16x32_bf16 v[12:15], v[152:155], v[220:223], v[12:15]
	s_setprio 0
	s_setprio 1
	v_mfma_f32_16x16x32_bf16 v[56:59], v[156:159], v[172:175], v[56:59]
	v_mfma_f32_16x16x32_bf16 v[52:55], v[164:167], v[172:175], v[52:55]
	v_mfma_f32_16x16x32_bf16 v[40:43], v[156:159], v[180:183], v[40:43]
	v_mfma_f32_16x16x32_bf16 v[36:39], v[164:167], v[180:183], v[36:39]
	v_mfma_f32_16x16x32_bf16 v[24:27], v[156:159], v[188:191], v[24:27]
	v_mfma_f32_16x16x32_bf16 v[20:23], v[164:167], v[188:191], v[20:23]
	v_mfma_f32_16x16x32_bf16 v[8:11], v[156:159], v[216:219], v[8:11]
	v_mfma_f32_16x16x32_bf16 v[4:7], v[164:167], v[216:219], v[4:7]
	v_mfma_f32_16x16x32_bf16 v[56:59], v[160:163], v[176:179], v[56:59]
	v_mfma_f32_16x16x32_bf16 v[52:55], v[168:171], v[176:179], v[52:55]
	v_mfma_f32_16x16x32_bf16 v[40:43], v[160:163], v[184:187], v[40:43]
	v_mfma_f32_16x16x32_bf16 v[36:39], v[168:171], v[184:187], v[36:39]
	v_mfma_f32_16x16x32_bf16 v[24:27], v[160:163], v[212:215], v[24:27]
	v_mfma_f32_16x16x32_bf16 v[20:23], v[168:171], v[212:215], v[20:23]
	v_mfma_f32_16x16x32_bf16 v[8:11], v[160:163], v[220:223], v[8:11]
	v_mfma_f32_16x16x32_bf16 v[4:7], v[168:171], v[220:223], v[4:7]
	s_setprio 0
	s_barrier
	s_add_i32 s7, s7, 2
	v_lshl_add_u64 v[138:139], v[138:139], 0, s[72:73]
	s_cmpk_gt_u32 s7, 0x7d
	v_lshl_add_u64 v[132:133], v[132:133], 0, s[72:73]
	s_cbranch_scc0 .LBB0_1268
	s_and_b64 vcc, exec, s[2:3]
	s_cbranch_vccz .LBB0_1271
	s_barrier
